# nt hint on the GEMM fast-path epilogue stores (RW/HG/OUT outputs are streamed out, keeps L2 for the A/B panels) on top of v134
# baseline (speedup 1.0000x reference)
.LBB0_66:
	ds_read_b128 v[158:161], v164
	ds_read_b128 v[180:183], v165
	ds_read_b128 v[184:187], v166
	ds_read_b128 v[188:191], v167
	s_add_u32 s6, s4, 0xfff7c080
	s_addc_u32 s7, s5, -1
	s_cmp_eq_u32 s53, 28
	s_cselect_b32 s21, s17, s7
	s_cselect_b32 s20, s16, s6
	s_cselect_b32 s7, s19, s23
	s_cselect_b32 s6, s18, s22
	s_mov_b32 m0, s37
	v_lshl_add_u64 v[224:225], s[4:5], 0, v[150:151]
	ds_read_b128 v[192:195], v137
	ds_read_b128 v[196:199], v137 offset:1024
	ds_read_b128 v[200:203], v137 offset:2048
	ds_read_b128 v[204:207], v137 offset:3072
	ds_read_b128 v[208:211], v137 offset:4096
	ds_read_b128 v[212:215], v137 offset:5120
	ds_read_b128 v[216:219], v137 offset:6144
	ds_read_b128 v[220:223], v137 offset:7168
	global_load_lds_dwordx4 v[224:225], off
	v_lshl_add_u64 v[224:225], s[4:5], 0, v[152:153]
	s_mov_b32 m0, s38
	s_nop 0
	global_load_lds_dwordx4 v[224:225], off
	s_waitcnt lgkmcnt(8)
	s_barrier
	s_waitcnt lgkmcnt(0)
	s_setprio 1
	s_waitcnt lgkmcnt(0)
	v_mfma_f32_16x16x32_bf16 v[124:127], v[158:161], v[192:195], v[124:127]
	v_mfma_f32_16x16x32_bf16 v[120:123], v[184:187], v[192:195], v[120:123]
	v_mfma_f32_16x16x32_bf16 v[108:111], v[158:161], v[200:203], v[108:111]
	v_mfma_f32_16x16x32_bf16 v[104:107], v[184:187], v[200:203], v[104:107]
	v_mfma_f32_16x16x32_bf16 v[92:95], v[158:161], v[208:211], v[92:95]
	v_mfma_f32_16x16x32_bf16 v[88:91], v[184:187], v[208:211], v[88:91]
	v_mfma_f32_16x16x32_bf16 v[76:79], v[158:161], v[216:219], v[76:79]
	v_mfma_f32_16x16x32_bf16 v[72:75], v[184:187], v[216:219], v[72:75]
	v_mfma_f32_16x16x32_bf16 v[124:127], v[180:183], v[196:199], v[124:127]
	v_mfma_f32_16x16x32_bf16 v[120:123], v[188:191], v[196:199], v[120:123]
	v_mfma_f32_16x16x32_bf16 v[108:111], v[180:183], v[204:207], v[108:111]
	v_mfma_f32_16x16x32_bf16 v[104:107], v[188:191], v[204:207], v[104:107]
	v_mfma_f32_16x16x32_bf16 v[92:95], v[180:183], v[212:215], v[92:95]
	v_mfma_f32_16x16x32_bf16 v[88:91], v[188:191], v[212:215], v[88:91]
	v_mfma_f32_16x16x32_bf16 v[76:79], v[180:183], v[220:223], v[76:79]
	v_mfma_f32_16x16x32_bf16 v[72:75], v[188:191], v[220:223], v[72:75]
	s_setprio 0
	s_barrier
	s_mov_b32 m0, s28
	v_lshl_add_u64 v[240:241], s[6:7], 0, v[130:131]
	ds_read_b128 v[224:227], v168
	ds_read_b128 v[228:231], v169
	ds_read_b128 v[232:235], v170
	ds_read_b128 v[236:239], v171
	global_load_lds_dwordx4 v[240:241], off
	v_lshl_add_u64 v[242:243], s[6:7], 0, v[132:133]
	s_mov_b32 m0, s29
	s_nop 0
	global_load_lds_dwordx4 v[242:243], off
	s_barrier
	s_waitcnt lgkmcnt(0)
	s_setprio 1
	s_waitcnt lgkmcnt(0)
	v_mfma_f32_16x16x32_bf16 v[116:119], v[224:227], v[192:195], v[116:119]
	v_mfma_f32_16x16x32_bf16 v[112:115], v[232:235], v[192:195], v[112:115]
	v_mfma_f32_16x16x32_bf16 v[100:103], v[224:227], v[200:203], v[100:103]
	v_mfma_f32_16x16x32_bf16 v[96:99], v[232:235], v[200:203], v[96:99]
	v_mfma_f32_16x16x32_bf16 v[84:87], v[224:227], v[208:211], v[84:87]
	v_mfma_f32_16x16x32_bf16 v[80:83], v[232:235], v[208:211], v[80:83]
	v_mfma_f32_16x16x32_bf16 v[68:71], v[224:227], v[216:219], v[68:71]
	v_mfma_f32_16x16x32_bf16 v[64:67], v[232:235], v[216:219], v[64:67]
	v_mfma_f32_16x16x32_bf16 v[116:119], v[228:231], v[196:199], v[116:119]
	v_mfma_f32_16x16x32_bf16 v[112:115], v[236:239], v[196:199], v[112:115]
	v_mfma_f32_16x16x32_bf16 v[100:103], v[228:231], v[204:207], v[100:103]
	v_mfma_f32_16x16x32_bf16 v[96:99], v[236:239], v[204:207], v[96:99]
	v_mfma_f32_16x16x32_bf16 v[84:87], v[228:231], v[212:215], v[84:87]
	v_mfma_f32_16x16x32_bf16 v[80:83], v[236:239], v[212:215], v[80:83]
	v_mfma_f32_16x16x32_bf16 v[68:71], v[228:231], v[220:223], v[68:71]
	v_mfma_f32_16x16x32_bf16 v[64:67], v[236:239], v[220:223], v[64:67]
	s_setprio 0
	s_mov_b32 m0, s40
	v_lshl_add_u64 v[244:245], s[20:21], 0, v[130:131]
	s_barrier
	ds_read_b128 v[192:195], v137 offset:16384
	ds_read_b128 v[196:199], v137 offset:17408
	ds_read_b128 v[200:203], v137 offset:18432
	ds_read_b128 v[204:207], v137 offset:19456
	ds_read_b128 v[208:211], v137 offset:20480
	ds_read_b128 v[212:215], v137 offset:21504
	ds_read_b128 v[216:219], v137 offset:22528
	ds_read_b128 v[220:223], v137 offset:23552
	global_load_lds_dwordx4 v[244:245], off
	v_lshl_add_u64 v[246:247], s[20:21], 0, v[132:133]
	s_mov_b32 m0, s30
	s_nop 0
	global_load_lds_dwordx4 v[246:247], off
	s_barrier
	s_waitcnt lgkmcnt(0)
	s_setprio 1
	s_waitcnt lgkmcnt(0)
	v_mfma_f32_16x16x32_bf16 v[60:63], v[158:161], v[192:195], v[60:63]
	v_mfma_f32_16x16x32_bf16 v[56:59], v[184:187], v[192:195], v[56:59]
	v_mfma_f32_16x16x32_bf16 v[44:47], v[158:161], v[200:203], v[44:47]
	v_mfma_f32_16x16x32_bf16 v[40:43], v[184:187], v[200:203], v[40:43]
	v_mfma_f32_16x16x32_bf16 v[28:31], v[158:161], v[208:211], v[28:31]
	v_mfma_f32_16x16x32_bf16 v[24:27], v[184:187], v[208:211], v[24:27]
	v_mfma_f32_16x16x32_bf16 v[12:15], v[158:161], v[216:219], v[12:15]
	v_mfma_f32_16x16x32_bf16 v[8:11], v[184:187], v[216:219], v[8:11]
	v_mfma_f32_16x16x32_bf16 v[60:63], v[180:183], v[196:199], v[60:63]
	v_mfma_f32_16x16x32_bf16 v[56:59], v[188:191], v[196:199], v[56:59]
	v_mfma_f32_16x16x32_bf16 v[44:47], v[180:183], v[204:207], v[44:47]
	v_mfma_f32_16x16x32_bf16 v[40:43], v[188:191], v[204:207], v[40:43]
	v_mfma_f32_16x16x32_bf16 v[28:31], v[180:183], v[212:215], v[28:31]
	v_mfma_f32_16x16x32_bf16 v[24:27], v[188:191], v[212:215], v[24:27]
	v_mfma_f32_16x16x32_bf16 v[12:15], v[180:183], v[220:223], v[12:15]
	v_mfma_f32_16x16x32_bf16 v[8:11], v[188:191], v[220:223], v[8:11]
	s_setprio 0
	s_barrier
	s_add_u32 s54, s6, 0x84000
	s_addc_u32 s55, s7, 0
	s_mov_b32 m0, s31
	v_lshl_add_u64 v[158:159], s[54:55], 0, v[130:131]
	global_load_lds_dwordx4 v[158:159], off
	v_lshl_add_u64 v[158:159], s[54:55], 0, v[132:133]
	s_mov_b32 m0, s33
	s_nop 0
	global_load_lds_dwordx4 v[158:159], off
	s_waitcnt vmcnt(6)
	s_barrier
	s_setprio 1
	v_mfma_f32_16x16x32_bf16 v[52:55], v[224:227], v[192:195], v[52:55]
	v_mfma_f32_16x16x32_bf16 v[48:51], v[232:235], v[192:195], v[48:51]
	v_mfma_f32_16x16x32_bf16 v[36:39], v[224:227], v[200:203], v[36:39]
	v_mfma_f32_16x16x32_bf16 v[32:35], v[232:235], v[200:203], v[32:35]
	v_mfma_f32_16x16x32_bf16 v[20:23], v[224:227], v[208:211], v[20:23]
	v_mfma_f32_16x16x32_bf16 v[16:19], v[232:235], v[208:211], v[16:19]
	v_mfma_f32_16x16x32_bf16 v[4:7], v[224:227], v[216:219], v[4:7]
	v_mfma_f32_16x16x32_bf16 v[0:3], v[232:235], v[216:219], v[0:3]
	v_mfma_f32_16x16x32_bf16 v[52:55], v[228:231], v[196:199], v[52:55]
	v_mfma_f32_16x16x32_bf16 v[48:51], v[236:239], v[196:199], v[48:51]
	v_mfma_f32_16x16x32_bf16 v[36:39], v[228:231], v[204:207], v[36:39]
	v_mfma_f32_16x16x32_bf16 v[32:35], v[236:239], v[204:207], v[32:35]
	v_mfma_f32_16x16x32_bf16 v[20:23], v[228:231], v[212:215], v[20:23]
	v_mfma_f32_16x16x32_bf16 v[16:19], v[236:239], v[212:215], v[16:19]
	v_mfma_f32_16x16x32_bf16 v[4:7], v[228:231], v[220:223], v[4:7]
	v_mfma_f32_16x16x32_bf16 v[0:3], v[236:239], v[220:223], v[0:3]
	s_setprio 0
	s_barrier
	ds_read_b128 v[158:161], v172
	ds_read_b128 v[180:183], v173
	ds_read_b128 v[184:187], v174
	ds_read_b128 v[188:191], v175
	s_add_u32 s20, s20, 0x84000
	s_addc_u32 s21, s21, 0
	s_mov_b32 m0, s34
	v_lshl_add_u64 v[224:225], s[20:21], 0, v[130:131]
	ds_read_b128 v[192:195], v137 offset:32768
	ds_read_b128 v[196:199], v137 offset:33792
	ds_read_b128 v[200:203], v137 offset:34816
	ds_read_b128 v[204:207], v137 offset:35840
	ds_read_b128 v[208:211], v137 offset:36864
	ds_read_b128 v[212:215], v137 offset:37888
	ds_read_b128 v[216:219], v137 offset:38912
	ds_read_b128 v[220:223], v137 offset:39936
	global_load_lds_dwordx4 v[224:225], off
	v_lshl_add_u64 v[224:225], s[20:21], 0, v[132:133]
	s_mov_b32 m0, s35
	s_nop 0
	global_load_lds_dwordx4 v[224:225], off
	s_waitcnt lgkmcnt(8)
	s_barrier
	s_waitcnt lgkmcnt(0)
	s_setprio 1
	s_waitcnt lgkmcnt(0)
	v_mfma_f32_16x16x32_bf16 v[124:127], v[158:161], v[192:195], v[124:127]
	v_mfma_f32_16x16x32_bf16 v[120:123], v[184:187], v[192:195], v[120:123]
	v_mfma_f32_16x16x32_bf16 v[108:111], v[158:161], v[200:203], v[108:111]
	v_mfma_f32_16x16x32_bf16 v[104:107], v[184:187], v[200:203], v[104:107]
	v_mfma_f32_16x16x32_bf16 v[92:95], v[158:161], v[208:211], v[92:95]
	v_mfma_f32_16x16x32_bf16 v[88:91], v[184:187], v[208:211], v[88:91]
	v_mfma_f32_16x16x32_bf16 v[76:79], v[158:161], v[216:219], v[76:79]
	v_mfma_f32_16x16x32_bf16 v[72:75], v[184:187], v[216:219], v[72:75]
	v_mfma_f32_16x16x32_bf16 v[124:127], v[180:183], v[196:199], v[124:127]
	v_mfma_f32_16x16x32_bf16 v[120:123], v[188:191], v[196:199], v[120:123]
	v_mfma_f32_16x16x32_bf16 v[108:111], v[180:183], v[204:207], v[108:111]
	v_mfma_f32_16x16x32_bf16 v[104:107], v[188:191], v[204:207], v[104:107]
	v_mfma_f32_16x16x32_bf16 v[92:95], v[180:183], v[212:215], v[92:95]
	v_mfma_f32_16x16x32_bf16 v[88:91], v[188:191], v[212:215], v[88:91]
	v_mfma_f32_16x16x32_bf16 v[76:79], v[180:183], v[220:223], v[76:79]
	v_mfma_f32_16x16x32_bf16 v[72:75], v[188:191], v[220:223], v[72:75]
	s_setprio 0
	s_barrier
	s_mov_b32 m0, s47
	v_lshl_add_u64 v[240:241], v[240:241], 0, s[10:11]
	ds_read_b128 v[224:227], v176
	ds_read_b128 v[228:231], v177
	ds_read_b128 v[232:235], v178
	ds_read_b128 v[236:239], v179
	global_load_lds_dwordx4 v[240:241], off
	v_lshl_add_u64 v[240:241], v[242:243], 0, s[10:11]
	s_mov_b32 m0, s48
	s_nop 0
	global_load_lds_dwordx4 v[240:241], off
	s_barrier
	s_waitcnt lgkmcnt(0)
	s_setprio 1
	s_waitcnt lgkmcnt(0)
	v_mfma_f32_16x16x32_bf16 v[116:119], v[224:227], v[192:195], v[116:119]
	v_mfma_f32_16x16x32_bf16 v[112:115], v[232:235], v[192:195], v[112:115]
	v_mfma_f32_16x16x32_bf16 v[100:103], v[224:227], v[200:203], v[100:103]
	v_mfma_f32_16x16x32_bf16 v[96:99], v[232:235], v[200:203], v[96:99]
	v_mfma_f32_16x16x32_bf16 v[84:87], v[224:227], v[208:211], v[84:87]
	v_mfma_f32_16x16x32_bf16 v[80:83], v[232:235], v[208:211], v[80:83]
	v_mfma_f32_16x16x32_bf16 v[68:71], v[224:227], v[216:219], v[68:71]
	v_mfma_f32_16x16x32_bf16 v[64:67], v[232:235], v[216:219], v[64:67]
	v_mfma_f32_16x16x32_bf16 v[116:119], v[228:231], v[196:199], v[116:119]
	v_mfma_f32_16x16x32_bf16 v[112:115], v[236:239], v[196:199], v[112:115]
	v_mfma_f32_16x16x32_bf16 v[100:103], v[228:231], v[204:207], v[100:103]
	v_mfma_f32_16x16x32_bf16 v[96:99], v[236:239], v[204:207], v[96:99]
	v_mfma_f32_16x16x32_bf16 v[84:87], v[228:231], v[212:215], v[84:87]
	v_mfma_f32_16x16x32_bf16 v[80:83], v[236:239], v[212:215], v[80:83]
	v_mfma_f32_16x16x32_bf16 v[68:71], v[228:231], v[220:223], v[68:71]
	v_mfma_f32_16x16x32_bf16 v[64:67], v[236:239], v[220:223], v[64:67]
	s_setprio 0
	s_mov_b32 m0, s49
	v_lshl_add_u64 v[240:241], v[244:245], 0, s[10:11]
	s_barrier
	ds_read_b128 v[192:195], v137 offset:49152
	ds_read_b128 v[196:199], v137 offset:50176
	ds_read_b128 v[200:203], v137 offset:51200
	ds_read_b128 v[204:207], v137 offset:52224
	ds_read_b128 v[208:211], v137 offset:53248
	ds_read_b128 v[212:215], v137 offset:54272
	ds_read_b128 v[216:219], v137 offset:55296
	ds_read_b128 v[220:223], v137 offset:56320
	global_load_lds_dwordx4 v[240:241], off
	v_lshl_add_u64 v[240:241], v[246:247], 0, s[10:11]
	s_mov_b32 m0, s50
	s_nop 0
	global_load_lds_dwordx4 v[240:241], off
	s_barrier
	s_waitcnt lgkmcnt(0)
	s_setprio 1
	s_waitcnt lgkmcnt(0)
	v_mfma_f32_16x16x32_bf16 v[60:63], v[158:161], v[192:195], v[60:63]
	v_mfma_f32_16x16x32_bf16 v[56:59], v[184:187], v[192:195], v[56:59]
	v_mfma_f32_16x16x32_bf16 v[44:47], v[158:161], v[200:203], v[44:47]
	v_mfma_f32_16x16x32_bf16 v[40:43], v[184:187], v[200:203], v[40:43]
	v_mfma_f32_16x16x32_bf16 v[28:31], v[158:161], v[208:211], v[28:31]
	v_mfma_f32_16x16x32_bf16 v[24:27], v[184:187], v[208:211], v[24:27]
	v_mfma_f32_16x16x32_bf16 v[12:15], v[158:161], v[216:219], v[12:15]
	v_mfma_f32_16x16x32_bf16 v[8:11], v[184:187], v[216:219], v[8:11]
	v_mfma_f32_16x16x32_bf16 v[60:63], v[180:183], v[196:199], v[60:63]
	v_mfma_f32_16x16x32_bf16 v[56:59], v[188:191], v[196:199], v[56:59]
	v_mfma_f32_16x16x32_bf16 v[44:47], v[180:183], v[204:207], v[44:47]
	v_mfma_f32_16x16x32_bf16 v[40:43], v[188:191], v[204:207], v[40:43]
	v_mfma_f32_16x16x32_bf16 v[28:31], v[180:183], v[212:215], v[28:31]
	v_mfma_f32_16x16x32_bf16 v[24:27], v[188:191], v[212:215], v[24:27]
	v_mfma_f32_16x16x32_bf16 v[12:15], v[180:183], v[220:223], v[12:15]
	v_mfma_f32_16x16x32_bf16 v[8:11], v[188:191], v[220:223], v[8:11]
	s_setprio 0
	s_barrier
	s_add_u32 s6, s6, 0x84080
	s_addc_u32 s7, s7, 0
	s_mov_b32 m0, s51
	v_lshl_add_u64 v[158:159], s[6:7], 0, v[130:131]
	global_load_lds_dwordx4 v[158:159], off
	v_lshl_add_u64 v[158:159], s[6:7], 0, v[132:133]
	s_mov_b32 m0, s27
	s_nop 0
	global_load_lds_dwordx4 v[158:159], off
	s_waitcnt vmcnt(6)
	s_barrier
	s_setprio 1
	v_mfma_f32_16x16x32_bf16 v[52:55], v[224:227], v[192:195], v[52:55]
	v_mfma_f32_16x16x32_bf16 v[48:51], v[232:235], v[192:195], v[48:51]
	v_mfma_f32_16x16x32_bf16 v[36:39], v[224:227], v[200:203], v[36:39]
	v_mfma_f32_16x16x32_bf16 v[32:35], v[232:235], v[200:203], v[32:35]
	v_mfma_f32_16x16x32_bf16 v[20:23], v[224:227], v[208:211], v[20:23]
	v_mfma_f32_16x16x32_bf16 v[16:19], v[232:235], v[208:211], v[16:19]
	v_mfma_f32_16x16x32_bf16 v[4:7], v[224:227], v[216:219], v[4:7]
	v_mfma_f32_16x16x32_bf16 v[0:3], v[232:235], v[216:219], v[0:3]
	v_mfma_f32_16x16x32_bf16 v[52:55], v[228:231], v[196:199], v[52:55]
	v_mfma_f32_16x16x32_bf16 v[48:51], v[236:239], v[196:199], v[48:51]
	v_mfma_f32_16x16x32_bf16 v[36:39], v[228:231], v[204:207], v[36:39]
	v_mfma_f32_16x16x32_bf16 v[32:35], v[236:239], v[204:207], v[32:35]
	v_mfma_f32_16x16x32_bf16 v[20:23], v[228:231], v[212:215], v[20:23]
	v_mfma_f32_16x16x32_bf16 v[16:19], v[236:239], v[212:215], v[16:19]
	v_mfma_f32_16x16x32_bf16 v[4:7], v[228:231], v[220:223], v[4:7]
	v_mfma_f32_16x16x32_bf16 v[0:3], v[236:239], v[220:223], v[0:3]
	s_setprio 0
	s_add_i32 s53, s53, 2
	s_add_u32 s4, s4, 0x100
	s_addc_u32 s5, s5, 0
	s_add_u32 s22, s22, 0x100
	s_addc_u32 s23, s23, 0
	s_cmp_gt_u32 s53, 29
	s_barrier
	s_cbranch_scc0 .LBB0_66
	s_cmp_lt_u32 s43, 0x80
	s_cbranch_scc0 .Lepi_rw_slow
	s_cmp_eq_u32 s43, 64
	s_cbranch_scc1 .Lepi_rw_slow
	s_cmp_eq_u32 s24, 0
	s_cbranch_scc1 .Lepi_rw_slow
	s_lshl_b32 s4, s43, 8
	s_add_i32 s4, s4, s46
	v_or_b32_e32 v180, s4, v134
	v_mad_i64_i32 v[160:161], s[6:7], v180, s41, 0
	v_lshrrev_b32_e32 v181, 2, v145
	v_and_b32_e32 v182, 1, v181
	v_bfe_u32 v183, v181, 1, 1
	v_and_b32_e32 v181, 0x60, v145
	v_lshlrev_b32_e32 v181, 1, v181
	v_lshl_add_u32 v181, v182, 5, v181
	v_lshl_add_u32 v181, v183, 4, v181
	s_lshl_b32 s5, s24, 9
	s_sub_i32 s5, s5, 0x100
	v_add_u32_e32 v181, s5, v181
	v_lshl_add_u64 v[160:161], s[72:73], 0, v[160:161]
	v_add_co_u32_e32 v184, vcc, v160, v181
	s_mov_b32 s20, 0x21000
	s_mov_b32 s21, 0
	v_addc_co_u32_e32 v185, vcc, 0, v161, vcc
	s_mov_b32 s22, 0xa5000
	s_mov_b32 s23, 0
	v_cvt_pk_bf16_f32 v192, v124, v125
	v_cvt_pk_bf16_f32 v193, v126, v127
	v_cvt_pk_bf16_f32 v194, v120, v121
	v_cvt_pk_bf16_f32 v195, v122, v123
	v_cvt_pk_bf16_f32 v196, v116, v117
	v_cvt_pk_bf16_f32 v197, v118, v119
	v_cvt_pk_bf16_f32 v198, v112, v113
	v_cvt_pk_bf16_f32 v199, v114, v115
	s_nop 0
	v_permlane16_swap_b32_e32 v192, v194
	v_permlane16_swap_b32_e32 v193, v195
	v_permlane16_swap_b32_e32 v196, v198
	v_permlane16_swap_b32_e32 v197, v199
	s_nop 0
	global_store_dwordx4 v[184:185], v[192:195], off nt
	global_store_dwordx4 v[184:185], v[196:199], off offset:256 nt
	v_lshl_add_u64 v[184:185], v[184:185], 0, s[20:21]
	v_cvt_pk_bf16_f32 v200, v108, v109
	v_cvt_pk_bf16_f32 v201, v110, v111
	v_cvt_pk_bf16_f32 v202, v104, v105
	v_cvt_pk_bf16_f32 v203, v106, v107
	v_cvt_pk_bf16_f32 v204, v100, v101
	v_cvt_pk_bf16_f32 v205, v102, v103
	v_cvt_pk_bf16_f32 v206, v96, v97
	v_cvt_pk_bf16_f32 v207, v98, v99
	s_nop 0
	v_permlane16_swap_b32_e32 v200, v202
	v_permlane16_swap_b32_e32 v201, v203
	v_permlane16_swap_b32_e32 v204, v206
	v_permlane16_swap_b32_e32 v205, v207
	s_nop 0
	global_store_dwordx4 v[184:185], v[200:203], off nt
	global_store_dwordx4 v[184:185], v[204:207], off offset:256 nt
	v_lshl_add_u64 v[184:185], v[184:185], 0, s[20:21]
	v_cvt_pk_bf16_f32 v208, v92, v93
	v_cvt_pk_bf16_f32 v209, v94, v95
	v_cvt_pk_bf16_f32 v210, v88, v89
	v_cvt_pk_bf16_f32 v211, v90, v91
	v_cvt_pk_bf16_f32 v212, v84, v85
	v_cvt_pk_bf16_f32 v213, v86, v87
	v_cvt_pk_bf16_f32 v214, v80, v81
	v_cvt_pk_bf16_f32 v215, v82, v83
	s_nop 0
	v_permlane16_swap_b32_e32 v208, v210
	v_permlane16_swap_b32_e32 v209, v211
	v_permlane16_swap_b32_e32 v212, v214
	v_permlane16_swap_b32_e32 v213, v215
	s_nop 0
	global_store_dwordx4 v[184:185], v[208:211], off nt
	global_store_dwordx4 v[184:185], v[212:215], off offset:256 nt
	v_lshl_add_u64 v[184:185], v[184:185], 0, s[20:21]
	v_cvt_pk_bf16_f32 v216, v76, v77
	v_cvt_pk_bf16_f32 v217, v78, v79
	v_cvt_pk_bf16_f32 v218, v72, v73
	v_cvt_pk_bf16_f32 v219, v74, v75
	v_cvt_pk_bf16_f32 v220, v68, v69
	v_cvt_pk_bf16_f32 v221, v70, v71
	v_cvt_pk_bf16_f32 v222, v64, v65
	v_cvt_pk_bf16_f32 v223, v66, v67
	s_nop 0
	v_permlane16_swap_b32_e32 v216, v218
	v_permlane16_swap_b32_e32 v217, v219
	v_permlane16_swap_b32_e32 v220, v222
	v_permlane16_swap_b32_e32 v221, v223
	s_nop 0
	global_store_dwordx4 v[184:185], v[216:219], off nt
	global_store_dwordx4 v[184:185], v[220:223], off offset:256 nt
	v_lshl_add_u64 v[184:185], v[184:185], 0, s[22:23]
	v_cvt_pk_bf16_f32 v192, v60, v61
	v_cvt_pk_bf16_f32 v193, v62, v63
	v_cvt_pk_bf16_f32 v194, v56, v57
	v_cvt_pk_bf16_f32 v195, v58, v59
	v_cvt_pk_bf16_f32 v196, v52, v53
	v_cvt_pk_bf16_f32 v197, v54, v55
	v_cvt_pk_bf16_f32 v198, v48, v49
	v_cvt_pk_bf16_f32 v199, v50, v51
	s_nop 0
	v_permlane16_swap_b32_e32 v192, v194
	v_permlane16_swap_b32_e32 v193, v195
	v_permlane16_swap_b32_e32 v196, v198
	v_permlane16_swap_b32_e32 v197, v199
	s_nop 0
	global_store_dwordx4 v[184:185], v[192:195], off nt
	global_store_dwordx4 v[184:185], v[196:199], off offset:256 nt
	v_lshl_add_u64 v[184:185], v[184:185], 0, s[20:21]
	v_cvt_pk_bf16_f32 v200, v44, v45
	v_cvt_pk_bf16_f32 v201, v46, v47
	v_cvt_pk_bf16_f32 v202, v40, v41
	v_cvt_pk_bf16_f32 v203, v42, v43
	v_cvt_pk_bf16_f32 v204, v36, v37
	v_cvt_pk_bf16_f32 v205, v38, v39
	v_cvt_pk_bf16_f32 v206, v32, v33
	v_cvt_pk_bf16_f32 v207, v34, v35
	s_nop 0
	v_permlane16_swap_b32_e32 v200, v202
	v_permlane16_swap_b32_e32 v201, v203
	v_permlane16_swap_b32_e32 v204, v206
	v_permlane16_swap_b32_e32 v205, v207
	s_nop 0
	global_store_dwordx4 v[184:185], v[200:203], off nt
	global_store_dwordx4 v[184:185], v[204:207], off offset:256 nt
	v_lshl_add_u64 v[184:185], v[184:185], 0, s[20:21]
	v_cvt_pk_bf16_f32 v208, v28, v29
	v_cvt_pk_bf16_f32 v209, v30, v31
	v_cvt_pk_bf16_f32 v210, v24, v25
	v_cvt_pk_bf16_f32 v211, v26, v27
	v_cvt_pk_bf16_f32 v212, v20, v21
	v_cvt_pk_bf16_f32 v213, v22, v23
	v_cvt_pk_bf16_f32 v214, v16, v17
	v_cvt_pk_bf16_f32 v215, v18, v19
	s_nop 0
	v_permlane16_swap_b32_e32 v208, v210
	v_permlane16_swap_b32_e32 v209, v211
	v_permlane16_swap_b32_e32 v212, v214
	v_permlane16_swap_b32_e32 v213, v215
	s_nop 0
	global_store_dwordx4 v[184:185], v[208:211], off nt
	global_store_dwordx4 v[184:185], v[212:215], off offset:256 nt
	v_lshl_add_u64 v[184:185], v[184:185], 0, s[20:21]
	v_cvt_pk_bf16_f32 v216, v12, v13
	v_cvt_pk_bf16_f32 v217, v14, v15
	v_cvt_pk_bf16_f32 v218, v8, v9
	v_cvt_pk_bf16_f32 v219, v10, v11
	v_cvt_pk_bf16_f32 v220, v4, v5
	v_cvt_pk_bf16_f32 v221, v6, v7
	v_cvt_pk_bf16_f32 v222, v0, v1
	v_cvt_pk_bf16_f32 v223, v2, v3
	s_nop 0
	v_permlane16_swap_b32_e32 v216, v218
	v_permlane16_swap_b32_e32 v217, v219
	v_permlane16_swap_b32_e32 v220, v222
	v_permlane16_swap_b32_e32 v221, v223
	s_nop 0
	global_store_dwordx4 v[184:185], v[216:219], off nt
	global_store_dwordx4 v[184:185], v[220:223], off offset:256 nt
	s_branch .LBB0_54

.LBB0_232:
	ds_read_b128 v[156:159], v167
	ds_read_b128 v[186:189], v168
	ds_read_b128 v[190:193], v169
	ds_read_b128 v[194:197], v170
	s_add_u32 s6, s4, 0xfff7c080
	s_addc_u32 s7, s5, -1
	s_cmp_eq_u32 s21, 28
	s_cselect_b32 s17, s13, s7
	s_cselect_b32 s16, s12, s6
	s_cselect_b32 s7, s15, s19
	s_cselect_b32 s6, s14, s18
	s_mov_b32 m0, s51
	v_lshl_add_u64 v[160:161], s[4:5], 0, v[148:149]
	ds_read_b128 v[198:201], v165
	ds_read_b128 v[202:205], v165 offset:1024
	ds_read_b128 v[206:209], v165 offset:2048
	ds_read_b128 v[210:213], v165 offset:3072
	ds_read_b128 v[214:217], v165 offset:4096
	ds_read_b128 v[218:221], v165 offset:5120
	ds_read_b128 v[222:225], v165 offset:6144
	ds_read_b128 v[226:229], v165 offset:7168
	global_load_lds_dwordx4 v[160:161], off
	v_lshl_add_u64 v[160:161], s[4:5], 0, v[150:151]
	s_mov_b32 m0, s38
	s_nop 0
	global_load_lds_dwordx4 v[160:161], off
	s_waitcnt lgkmcnt(8)
	s_barrier
	s_waitcnt lgkmcnt(0)
	s_setprio 1
	s_waitcnt lgkmcnt(0)
	v_mfma_f32_16x16x32_bf16 v[124:127], v[156:159], v[198:201], v[124:127]
	v_mfma_f32_16x16x32_bf16 v[120:123], v[190:193], v[198:201], v[120:123]
	v_mfma_f32_16x16x32_bf16 v[108:111], v[156:159], v[206:209], v[108:111]
	v_mfma_f32_16x16x32_bf16 v[104:107], v[190:193], v[206:209], v[104:107]
	v_mfma_f32_16x16x32_bf16 v[92:95], v[156:159], v[214:217], v[92:95]
	v_mfma_f32_16x16x32_bf16 v[88:91], v[190:193], v[214:217], v[88:91]
	v_mfma_f32_16x16x32_bf16 v[76:79], v[156:159], v[222:225], v[76:79]
	v_mfma_f32_16x16x32_bf16 v[72:75], v[190:193], v[222:225], v[72:75]
	v_mfma_f32_16x16x32_bf16 v[124:127], v[186:189], v[202:205], v[124:127]
	v_mfma_f32_16x16x32_bf16 v[120:123], v[194:197], v[202:205], v[120:123]
	v_mfma_f32_16x16x32_bf16 v[108:111], v[186:189], v[210:213], v[108:111]
	v_mfma_f32_16x16x32_bf16 v[104:107], v[194:197], v[210:213], v[104:107]
	v_mfma_f32_16x16x32_bf16 v[92:95], v[186:189], v[218:221], v[92:95]
	v_mfma_f32_16x16x32_bf16 v[88:91], v[194:197], v[218:221], v[88:91]
	v_mfma_f32_16x16x32_bf16 v[76:79], v[186:189], v[226:229], v[76:79]
	v_mfma_f32_16x16x32_bf16 v[72:75], v[194:197], v[226:229], v[72:75]
	s_setprio 0
	s_barrier
	s_mov_b32 m0, s24
	v_lshl_add_u64 v[160:161], s[6:7], 0, v[130:131]
	ds_read_b128 v[230:233], v171
	ds_read_b128 v[234:237], v172
	ds_read_b128 v[238:241], v173
	ds_read_b128 v[242:245], v174
	global_load_lds_dwordx4 v[160:161], off
	v_lshl_add_u64 v[246:247], s[6:7], 0, v[132:133]
	s_mov_b32 m0, s25
	s_nop 0
	global_load_lds_dwordx4 v[246:247], off
	s_barrier
	s_waitcnt lgkmcnt(0)
	s_setprio 1
	s_waitcnt lgkmcnt(0)
	v_mfma_f32_16x16x32_bf16 v[116:119], v[230:233], v[198:201], v[116:119]
	v_mfma_f32_16x16x32_bf16 v[112:115], v[238:241], v[198:201], v[112:115]
	v_mfma_f32_16x16x32_bf16 v[100:103], v[230:233], v[206:209], v[100:103]
	v_mfma_f32_16x16x32_bf16 v[96:99], v[238:241], v[206:209], v[96:99]
	v_mfma_f32_16x16x32_bf16 v[84:87], v[230:233], v[214:217], v[84:87]
	v_mfma_f32_16x16x32_bf16 v[80:83], v[238:241], v[214:217], v[80:83]
	v_mfma_f32_16x16x32_bf16 v[68:71], v[230:233], v[222:225], v[68:71]
	v_mfma_f32_16x16x32_bf16 v[64:67], v[238:241], v[222:225], v[64:67]
	v_mfma_f32_16x16x32_bf16 v[116:119], v[234:237], v[202:205], v[116:119]
	v_mfma_f32_16x16x32_bf16 v[112:115], v[242:245], v[202:205], v[112:115]
	v_mfma_f32_16x16x32_bf16 v[100:103], v[234:237], v[210:213], v[100:103]
	v_mfma_f32_16x16x32_bf16 v[96:99], v[242:245], v[210:213], v[96:99]
	v_mfma_f32_16x16x32_bf16 v[84:87], v[234:237], v[218:221], v[84:87]
	v_mfma_f32_16x16x32_bf16 v[80:83], v[242:245], v[218:221], v[80:83]
	v_mfma_f32_16x16x32_bf16 v[68:71], v[234:237], v[226:229], v[68:71]
	v_mfma_f32_16x16x32_bf16 v[64:67], v[242:245], v[226:229], v[64:67]
	s_setprio 0
	s_mov_b32 m0, s23
	v_lshl_add_u64 v[248:249], s[16:17], 0, v[130:131]
	s_barrier
	ds_read_b128 v[198:201], v165 offset:16384
	ds_read_b128 v[202:205], v165 offset:17408
	ds_read_b128 v[206:209], v165 offset:18432
	ds_read_b128 v[210:213], v165 offset:19456
	ds_read_b128 v[214:217], v165 offset:20480
	ds_read_b128 v[218:221], v165 offset:21504
	ds_read_b128 v[222:225], v165 offset:22528
	ds_read_b128 v[226:229], v165 offset:23552
	global_load_lds_dwordx4 v[248:249], off
	v_lshl_add_u64 v[250:251], s[16:17], 0, v[132:133]
	s_mov_b32 m0, s26
	s_nop 0
	global_load_lds_dwordx4 v[250:251], off
	s_barrier
	s_waitcnt lgkmcnt(0)
	s_setprio 1
	s_waitcnt lgkmcnt(0)
	v_mfma_f32_16x16x32_bf16 v[60:63], v[156:159], v[198:201], v[60:63]
	v_mfma_f32_16x16x32_bf16 v[56:59], v[190:193], v[198:201], v[56:59]
	v_mfma_f32_16x16x32_bf16 v[44:47], v[156:159], v[206:209], v[44:47]
	v_mfma_f32_16x16x32_bf16 v[40:43], v[190:193], v[206:209], v[40:43]
	v_mfma_f32_16x16x32_bf16 v[28:31], v[156:159], v[214:217], v[28:31]
	v_mfma_f32_16x16x32_bf16 v[24:27], v[190:193], v[214:217], v[24:27]
	v_mfma_f32_16x16x32_bf16 v[12:15], v[156:159], v[222:225], v[12:15]
	v_mfma_f32_16x16x32_bf16 v[8:11], v[190:193], v[222:225], v[8:11]
	v_mfma_f32_16x16x32_bf16 v[60:63], v[186:189], v[202:205], v[60:63]
	v_mfma_f32_16x16x32_bf16 v[56:59], v[194:197], v[202:205], v[56:59]
	v_mfma_f32_16x16x32_bf16 v[44:47], v[186:189], v[210:213], v[44:47]
	v_mfma_f32_16x16x32_bf16 v[40:43], v[194:197], v[210:213], v[40:43]
	v_mfma_f32_16x16x32_bf16 v[28:31], v[186:189], v[218:221], v[28:31]
	v_mfma_f32_16x16x32_bf16 v[24:27], v[194:197], v[218:221], v[24:27]
	v_mfma_f32_16x16x32_bf16 v[12:15], v[186:189], v[226:229], v[12:15]
	v_mfma_f32_16x16x32_bf16 v[8:11], v[194:197], v[226:229], v[8:11]
	s_setprio 0
	s_barrier
	s_add_u32 s36, s6, 0x84000
	s_addc_u32 s37, s7, 0
	s_mov_b32 m0, s27
	v_lshl_add_u64 v[156:157], s[36:37], 0, v[130:131]
	global_load_lds_dwordx4 v[156:157], off
	v_lshl_add_u64 v[156:157], s[36:37], 0, v[132:133]
	s_mov_b32 m0, s28
	s_nop 0
	global_load_lds_dwordx4 v[156:157], off
	s_waitcnt vmcnt(6)
	s_barrier
	s_setprio 1
	v_mfma_f32_16x16x32_bf16 v[52:55], v[230:233], v[198:201], v[52:55]
	v_mfma_f32_16x16x32_bf16 v[48:51], v[238:241], v[198:201], v[48:51]
	v_mfma_f32_16x16x32_bf16 v[36:39], v[230:233], v[206:209], v[36:39]
	v_mfma_f32_16x16x32_bf16 v[32:35], v[238:241], v[206:209], v[32:35]
	v_mfma_f32_16x16x32_bf16 v[20:23], v[230:233], v[214:217], v[20:23]
	v_mfma_f32_16x16x32_bf16 v[16:19], v[238:241], v[214:217], v[16:19]
	v_mfma_f32_16x16x32_bf16 v[4:7], v[230:233], v[222:225], v[4:7]
	v_mfma_f32_16x16x32_bf16 v[0:3], v[238:241], v[222:225], v[0:3]
	v_mfma_f32_16x16x32_bf16 v[52:55], v[234:237], v[202:205], v[52:55]
	v_mfma_f32_16x16x32_bf16 v[48:51], v[242:245], v[202:205], v[48:51]
	v_mfma_f32_16x16x32_bf16 v[36:39], v[234:237], v[210:213], v[36:39]
	v_mfma_f32_16x16x32_bf16 v[32:35], v[242:245], v[210:213], v[32:35]
	v_mfma_f32_16x16x32_bf16 v[20:23], v[234:237], v[218:221], v[20:23]
	v_mfma_f32_16x16x32_bf16 v[16:19], v[242:245], v[218:221], v[16:19]
	v_mfma_f32_16x16x32_bf16 v[4:7], v[234:237], v[226:229], v[4:7]
	v_mfma_f32_16x16x32_bf16 v[0:3], v[242:245], v[226:229], v[0:3]
	s_setprio 0
	s_barrier
	ds_read_b128 v[156:159], v175
	ds_read_b128 v[186:189], v176
	ds_read_b128 v[190:193], v177
	ds_read_b128 v[194:197], v178
	s_add_u32 s16, s16, 0x84000
	s_addc_u32 s17, s17, 0
	s_mov_b32 m0, s29
	v_lshl_add_u64 v[230:231], s[16:17], 0, v[130:131]
	ds_read_b128 v[198:201], v165 offset:32768
	ds_read_b128 v[202:205], v165 offset:33792
	ds_read_b128 v[206:209], v165 offset:34816
	ds_read_b128 v[210:213], v165 offset:35840
	ds_read_b128 v[214:217], v165 offset:36864
	ds_read_b128 v[218:221], v165 offset:37888
	ds_read_b128 v[222:225], v165 offset:38912
	ds_read_b128 v[226:229], v165 offset:39936
	global_load_lds_dwordx4 v[230:231], off
	v_lshl_add_u64 v[230:231], s[16:17], 0, v[132:133]
	s_mov_b32 m0, s30
	s_nop 0
	global_load_lds_dwordx4 v[230:231], off
	s_waitcnt lgkmcnt(8)
	s_barrier
	s_waitcnt lgkmcnt(0)
	s_setprio 1
	s_waitcnt lgkmcnt(0)
	v_mfma_f32_16x16x32_bf16 v[124:127], v[156:159], v[198:201], v[124:127]
	v_mfma_f32_16x16x32_bf16 v[120:123], v[190:193], v[198:201], v[120:123]
	v_mfma_f32_16x16x32_bf16 v[108:111], v[156:159], v[206:209], v[108:111]
	v_mfma_f32_16x16x32_bf16 v[104:107], v[190:193], v[206:209], v[104:107]
	v_mfma_f32_16x16x32_bf16 v[92:95], v[156:159], v[214:217], v[92:95]
	v_mfma_f32_16x16x32_bf16 v[88:91], v[190:193], v[214:217], v[88:91]
	v_mfma_f32_16x16x32_bf16 v[76:79], v[156:159], v[222:225], v[76:79]
	v_mfma_f32_16x16x32_bf16 v[72:75], v[190:193], v[222:225], v[72:75]
	v_mfma_f32_16x16x32_bf16 v[124:127], v[186:189], v[202:205], v[124:127]
	v_mfma_f32_16x16x32_bf16 v[120:123], v[194:197], v[202:205], v[120:123]
	v_mfma_f32_16x16x32_bf16 v[108:111], v[186:189], v[210:213], v[108:111]
	v_mfma_f32_16x16x32_bf16 v[104:107], v[194:197], v[210:213], v[104:107]
	v_mfma_f32_16x16x32_bf16 v[92:95], v[186:189], v[218:221], v[92:95]
	v_mfma_f32_16x16x32_bf16 v[88:91], v[194:197], v[218:221], v[88:91]
	v_mfma_f32_16x16x32_bf16 v[76:79], v[186:189], v[226:229], v[76:79]
	v_mfma_f32_16x16x32_bf16 v[72:75], v[194:197], v[226:229], v[72:75]
	s_setprio 0
	s_barrier
	s_mov_b32 m0, s31
	v_lshl_add_u64 v[160:161], v[160:161], 0, s[10:11]
	ds_read_b128 v[230:233], v179
	ds_read_b128 v[234:237], v180
	ds_read_b128 v[238:241], v181
	ds_read_b128 v[242:245], v182
	global_load_lds_dwordx4 v[160:161], off
	v_lshl_add_u64 v[160:161], v[246:247], 0, s[10:11]
	s_mov_b32 m0, s34
	s_nop 0
	global_load_lds_dwordx4 v[160:161], off
	s_barrier
	s_waitcnt lgkmcnt(0)
	s_setprio 1
	s_waitcnt lgkmcnt(0)
	v_mfma_f32_16x16x32_bf16 v[116:119], v[230:233], v[198:201], v[116:119]
	v_mfma_f32_16x16x32_bf16 v[112:115], v[238:241], v[198:201], v[112:115]
	v_mfma_f32_16x16x32_bf16 v[100:103], v[230:233], v[206:209], v[100:103]
	v_mfma_f32_16x16x32_bf16 v[96:99], v[238:241], v[206:209], v[96:99]
	v_mfma_f32_16x16x32_bf16 v[84:87], v[230:233], v[214:217], v[84:87]
	v_mfma_f32_16x16x32_bf16 v[80:83], v[238:241], v[214:217], v[80:83]
	v_mfma_f32_16x16x32_bf16 v[68:71], v[230:233], v[222:225], v[68:71]
	v_mfma_f32_16x16x32_bf16 v[64:67], v[238:241], v[222:225], v[64:67]
	v_mfma_f32_16x16x32_bf16 v[116:119], v[234:237], v[202:205], v[116:119]
	v_mfma_f32_16x16x32_bf16 v[112:115], v[242:245], v[202:205], v[112:115]
	v_mfma_f32_16x16x32_bf16 v[100:103], v[234:237], v[210:213], v[100:103]
	v_mfma_f32_16x16x32_bf16 v[96:99], v[242:245], v[210:213], v[96:99]
	v_mfma_f32_16x16x32_bf16 v[84:87], v[234:237], v[218:221], v[84:87]
	v_mfma_f32_16x16x32_bf16 v[80:83], v[242:245], v[218:221], v[80:83]
	v_mfma_f32_16x16x32_bf16 v[68:71], v[234:237], v[226:229], v[68:71]
	v_mfma_f32_16x16x32_bf16 v[64:67], v[242:245], v[226:229], v[64:67]
	s_setprio 0
	s_mov_b32 m0, s35
	v_lshl_add_u64 v[160:161], v[248:249], 0, s[10:11]
	s_barrier
	ds_read_b128 v[198:201], v165 offset:49152
	ds_read_b128 v[202:205], v165 offset:50176
	ds_read_b128 v[206:209], v165 offset:51200
	ds_read_b128 v[210:213], v165 offset:52224
	ds_read_b128 v[214:217], v165 offset:53248
	ds_read_b128 v[218:221], v165 offset:54272
	ds_read_b128 v[222:225], v165 offset:55296
	ds_read_b128 v[226:229], v165 offset:56320
	global_load_lds_dwordx4 v[160:161], off
	v_lshl_add_u64 v[160:161], v[250:251], 0, s[10:11]
	s_mov_b32 m0, s44
	s_nop 0
	global_load_lds_dwordx4 v[160:161], off
	s_barrier
	s_waitcnt lgkmcnt(0)
	s_setprio 1
	s_waitcnt lgkmcnt(0)
	v_mfma_f32_16x16x32_bf16 v[60:63], v[156:159], v[198:201], v[60:63]
	v_mfma_f32_16x16x32_bf16 v[56:59], v[190:193], v[198:201], v[56:59]
	v_mfma_f32_16x16x32_bf16 v[44:47], v[156:159], v[206:209], v[44:47]
	v_mfma_f32_16x16x32_bf16 v[40:43], v[190:193], v[206:209], v[40:43]
	v_mfma_f32_16x16x32_bf16 v[28:31], v[156:159], v[214:217], v[28:31]
	v_mfma_f32_16x16x32_bf16 v[24:27], v[190:193], v[214:217], v[24:27]
	v_mfma_f32_16x16x32_bf16 v[12:15], v[156:159], v[222:225], v[12:15]
	v_mfma_f32_16x16x32_bf16 v[8:11], v[190:193], v[222:225], v[8:11]
	v_mfma_f32_16x16x32_bf16 v[60:63], v[186:189], v[202:205], v[60:63]
	v_mfma_f32_16x16x32_bf16 v[56:59], v[194:197], v[202:205], v[56:59]
	v_mfma_f32_16x16x32_bf16 v[44:47], v[186:189], v[210:213], v[44:47]
	v_mfma_f32_16x16x32_bf16 v[40:43], v[194:197], v[210:213], v[40:43]
	v_mfma_f32_16x16x32_bf16 v[28:31], v[186:189], v[218:221], v[28:31]
	v_mfma_f32_16x16x32_bf16 v[24:27], v[194:197], v[218:221], v[24:27]
	v_mfma_f32_16x16x32_bf16 v[12:15], v[186:189], v[226:229], v[12:15]
	v_mfma_f32_16x16x32_bf16 v[8:11], v[194:197], v[226:229], v[8:11]
	s_setprio 0
	s_barrier
	s_add_u32 s6, s6, 0x84080
	s_addc_u32 s7, s7, 0
	s_mov_b32 m0, s45
	v_lshl_add_u64 v[156:157], s[6:7], 0, v[130:131]
	global_load_lds_dwordx4 v[156:157], off
	v_lshl_add_u64 v[156:157], s[6:7], 0, v[132:133]
	s_mov_b32 m0, s46
	s_nop 0
	global_load_lds_dwordx4 v[156:157], off
	s_waitcnt vmcnt(6)
	s_barrier
	s_setprio 1
	v_mfma_f32_16x16x32_bf16 v[52:55], v[230:233], v[198:201], v[52:55]
	v_mfma_f32_16x16x32_bf16 v[48:51], v[238:241], v[198:201], v[48:51]
	v_mfma_f32_16x16x32_bf16 v[36:39], v[230:233], v[206:209], v[36:39]
	v_mfma_f32_16x16x32_bf16 v[32:35], v[238:241], v[206:209], v[32:35]
	v_mfma_f32_16x16x32_bf16 v[20:23], v[230:233], v[214:217], v[20:23]
	v_mfma_f32_16x16x32_bf16 v[16:19], v[238:241], v[214:217], v[16:19]
	v_mfma_f32_16x16x32_bf16 v[4:7], v[230:233], v[222:225], v[4:7]
	v_mfma_f32_16x16x32_bf16 v[0:3], v[238:241], v[222:225], v[0:3]
	v_mfma_f32_16x16x32_bf16 v[52:55], v[234:237], v[202:205], v[52:55]
	v_mfma_f32_16x16x32_bf16 v[48:51], v[242:245], v[202:205], v[48:51]
	v_mfma_f32_16x16x32_bf16 v[36:39], v[234:237], v[210:213], v[36:39]
	v_mfma_f32_16x16x32_bf16 v[32:35], v[242:245], v[210:213], v[32:35]
	v_mfma_f32_16x16x32_bf16 v[20:23], v[234:237], v[218:221], v[20:23]
	v_mfma_f32_16x16x32_bf16 v[16:19], v[242:245], v[218:221], v[16:19]
	v_mfma_f32_16x16x32_bf16 v[4:7], v[234:237], v[226:229], v[4:7]
	v_mfma_f32_16x16x32_bf16 v[0:3], v[242:245], v[226:229], v[0:3]
	s_setprio 0
	s_add_i32 s21, s21, 2
	s_add_u32 s4, s4, 0x100
	s_addc_u32 s5, s5, 0
	s_add_u32 s18, s18, 0x100
	s_addc_u32 s19, s19, 0
	s_cmp_gt_u32 s21, 29
	s_barrier
	s_cbranch_scc0 .LBB0_232
	s_cmp_lt_u32 s20, 0x88
	s_cbranch_scc0 .Lepi_hg_slow
	v_lshl_add_u32 v160, s20, 8, v143
	v_mov_b64_e32 v[156:157], s[72:73]
	v_mad_i64_i32 v[158:159], s[4:5], v160, s40, v[156:157]
	v_lshrrev_b32_e32 v160, 2, v166
	v_and_b32_e32 v161, 1, v160
	v_bfe_u32 v186, v160, 1, 1
	v_and_b32_e32 v160, 0x60, v166
	v_lshlrev_b32_e32 v160, 1, v160
	v_lshl_add_u32 v160, v161, 5, v160
	v_lshl_add_u32 v160, v186, 4, v160
	s_lshl_b32 s5, s2, 9
	v_add_u32_e32 v160, s5, v160
	s_mov_b32 s16, 0x20800
	v_add_co_u32_e32 v158, vcc, v158, v160
	s_mov_b32 s17, 0
	s_mov_b32 s18, 0xa2800
	v_addc_co_u32_e32 v159, vcc, 0, v159, vcc
	s_mov_b32 s19, 0
	s_lshr_b32 s4, s2, 2
	s_cmp_eq_u32 s4, 2
	s_cbranch_scc1 .Lepi_hg_copy
	s_cmp_eq_u32 s4, 1
	s_cbranch_scc1 .Lepi_hg_forget
	v_mul_f32_e32 v186, 0xbfb8aa3b, v124
	v_mul_f32_e32 v187, 0xbfb8aa3b, v125
	v_mul_f32_e32 v188, 0xbfb8aa3b, v126
	v_mul_f32_e32 v189, 0xbfb8aa3b, v127
	v_mul_f32_e32 v190, 0xbfb8aa3b, v120
	v_mul_f32_e32 v191, 0xbfb8aa3b, v121
	v_mul_f32_e32 v192, 0xbfb8aa3b, v122
	v_mul_f32_e32 v193, 0xbfb8aa3b, v123
	v_exp_f32_e32 v186, v186
	v_exp_f32_e32 v187, v187
	v_exp_f32_e32 v188, v188
	v_exp_f32_e32 v189, v189
	v_exp_f32_e32 v190, v190
	v_exp_f32_e32 v191, v191
	v_exp_f32_e32 v192, v192
	v_exp_f32_e32 v193, v193
	v_add_f32_e32 v186, 1.0, v186
	v_add_f32_e32 v187, 1.0, v187
	v_add_f32_e32 v188, 1.0, v188
	v_add_f32_e32 v189, 1.0, v189
	v_add_f32_e32 v190, 1.0, v190
	v_add_f32_e32 v191, 1.0, v191
	v_add_f32_e32 v192, 1.0, v192
	v_add_f32_e32 v193, 1.0, v193
	v_rcp_f32_e32 v186, v186
	v_rcp_f32_e32 v187, v187
	v_rcp_f32_e32 v188, v188
	v_rcp_f32_e32 v189, v189
	v_rcp_f32_e32 v190, v190
	v_rcp_f32_e32 v191, v191
	v_rcp_f32_e32 v192, v192
	v_rcp_f32_e32 v193, v193
	v_pk_mul_f32 v[186:187], v[124:125], v[186:187]
	v_pk_mul_f32 v[188:189], v[126:127], v[188:189]
	v_pk_mul_f32 v[190:191], v[120:121], v[190:191]
	v_pk_mul_f32 v[192:193], v[122:123], v[192:193]
	v_cvt_pk_bf16_f32 v194, v186, v187
	v_cvt_pk_bf16_f32 v195, v188, v189
	v_cvt_pk_bf16_f32 v196, v190, v191
	v_cvt_pk_bf16_f32 v197, v192, v193
	v_mul_f32_e32 v186, 0xbfb8aa3b, v116
	v_mul_f32_e32 v187, 0xbfb8aa3b, v117
	v_mul_f32_e32 v188, 0xbfb8aa3b, v118
	v_mul_f32_e32 v189, 0xbfb8aa3b, v119
	v_mul_f32_e32 v190, 0xbfb8aa3b, v112
	v_mul_f32_e32 v191, 0xbfb8aa3b, v113
	v_mul_f32_e32 v192, 0xbfb8aa3b, v114
	v_mul_f32_e32 v193, 0xbfb8aa3b, v115
	v_exp_f32_e32 v186, v186
	v_exp_f32_e32 v187, v187
	v_exp_f32_e32 v188, v188
	v_exp_f32_e32 v189, v189
	v_exp_f32_e32 v190, v190
	v_exp_f32_e32 v191, v191
	v_exp_f32_e32 v192, v192
	v_exp_f32_e32 v193, v193
	v_add_f32_e32 v186, 1.0, v186
	v_add_f32_e32 v187, 1.0, v187
	v_add_f32_e32 v188, 1.0, v188
	v_add_f32_e32 v189, 1.0, v189
	v_add_f32_e32 v190, 1.0, v190
	v_add_f32_e32 v191, 1.0, v191
	v_add_f32_e32 v192, 1.0, v192
	v_add_f32_e32 v193, 1.0, v193
	v_rcp_f32_e32 v186, v186
	v_rcp_f32_e32 v187, v187
	v_rcp_f32_e32 v188, v188
	v_rcp_f32_e32 v189, v189
	v_rcp_f32_e32 v190, v190
	v_rcp_f32_e32 v191, v191
	v_rcp_f32_e32 v192, v192
	v_rcp_f32_e32 v193, v193
	v_pk_mul_f32 v[186:187], v[116:117], v[186:187]
	v_pk_mul_f32 v[188:189], v[118:119], v[188:189]
	v_pk_mul_f32 v[190:191], v[112:113], v[190:191]
	v_pk_mul_f32 v[192:193], v[114:115], v[192:193]
	v_cvt_pk_bf16_f32 v198, v186, v187
	v_cvt_pk_bf16_f32 v199, v188, v189
	v_cvt_pk_bf16_f32 v200, v190, v191
	v_cvt_pk_bf16_f32 v201, v192, v193
	s_nop 0
	v_permlane16_swap_b32_e32 v194, v196
	v_permlane16_swap_b32_e32 v195, v197
	v_permlane16_swap_b32_e32 v198, v200
	v_permlane16_swap_b32_e32 v199, v201
	s_nop 0
	global_store_dwordx4 v[158:159], v[194:197], off nt
	global_store_dwordx4 v[158:159], v[198:201], off offset:256 nt
	v_lshl_add_u64 v[158:159], v[158:159], 0, s[16:17]
	v_mul_f32_e32 v186, 0xbfb8aa3b, v108
	v_mul_f32_e32 v187, 0xbfb8aa3b, v109
	v_mul_f32_e32 v188, 0xbfb8aa3b, v110
	v_mul_f32_e32 v189, 0xbfb8aa3b, v111
	v_mul_f32_e32 v190, 0xbfb8aa3b, v104
	v_mul_f32_e32 v191, 0xbfb8aa3b, v105
	v_mul_f32_e32 v192, 0xbfb8aa3b, v106
	v_mul_f32_e32 v193, 0xbfb8aa3b, v107
	v_exp_f32_e32 v186, v186
	v_exp_f32_e32 v187, v187
	v_exp_f32_e32 v188, v188
	v_exp_f32_e32 v189, v189
	v_exp_f32_e32 v190, v190
	v_exp_f32_e32 v191, v191
	v_exp_f32_e32 v192, v192
	v_exp_f32_e32 v193, v193
	v_add_f32_e32 v186, 1.0, v186
	v_add_f32_e32 v187, 1.0, v187
	v_add_f32_e32 v188, 1.0, v188
	v_add_f32_e32 v189, 1.0, v189
	v_add_f32_e32 v190, 1.0, v190
	v_add_f32_e32 v191, 1.0, v191
	v_add_f32_e32 v192, 1.0, v192
	v_add_f32_e32 v193, 1.0, v193
	v_rcp_f32_e32 v186, v186
	v_rcp_f32_e32 v187, v187
	v_rcp_f32_e32 v188, v188
	v_rcp_f32_e32 v189, v189
	v_rcp_f32_e32 v190, v190
	v_rcp_f32_e32 v191, v191
	v_rcp_f32_e32 v192, v192
	v_rcp_f32_e32 v193, v193
	v_pk_mul_f32 v[186:187], v[108:109], v[186:187]
	v_pk_mul_f32 v[188:189], v[110:111], v[188:189]
	v_pk_mul_f32 v[190:191], v[104:105], v[190:191]
	v_pk_mul_f32 v[192:193], v[106:107], v[192:193]
	v_cvt_pk_bf16_f32 v202, v186, v187
	v_cvt_pk_bf16_f32 v203, v188, v189
	v_cvt_pk_bf16_f32 v204, v190, v191
	v_cvt_pk_bf16_f32 v205, v192, v193
	v_mul_f32_e32 v186, 0xbfb8aa3b, v100
	v_mul_f32_e32 v187, 0xbfb8aa3b, v101
	v_mul_f32_e32 v188, 0xbfb8aa3b, v102
	v_mul_f32_e32 v189, 0xbfb8aa3b, v103
	v_mul_f32_e32 v190, 0xbfb8aa3b, v96
	v_mul_f32_e32 v191, 0xbfb8aa3b, v97
	v_mul_f32_e32 v192, 0xbfb8aa3b, v98
	v_mul_f32_e32 v193, 0xbfb8aa3b, v99
	v_exp_f32_e32 v186, v186
	v_exp_f32_e32 v187, v187
	v_exp_f32_e32 v188, v188
	v_exp_f32_e32 v189, v189
	v_exp_f32_e32 v190, v190
	v_exp_f32_e32 v191, v191
	v_exp_f32_e32 v192, v192
	v_exp_f32_e32 v193, v193
	v_add_f32_e32 v186, 1.0, v186
	v_add_f32_e32 v187, 1.0, v187
	v_add_f32_e32 v188, 1.0, v188
	v_add_f32_e32 v189, 1.0, v189
	v_add_f32_e32 v190, 1.0, v190
	v_add_f32_e32 v191, 1.0, v191
	v_add_f32_e32 v192, 1.0, v192
	v_add_f32_e32 v193, 1.0, v193
	v_rcp_f32_e32 v186, v186
	v_rcp_f32_e32 v187, v187
	v_rcp_f32_e32 v188, v188
	v_rcp_f32_e32 v189, v189
	v_rcp_f32_e32 v190, v190
	v_rcp_f32_e32 v191, v191
	v_rcp_f32_e32 v192, v192
	v_rcp_f32_e32 v193, v193
	v_pk_mul_f32 v[186:187], v[100:101], v[186:187]
	v_pk_mul_f32 v[188:189], v[102:103], v[188:189]
	v_pk_mul_f32 v[190:191], v[96:97], v[190:191]
	v_pk_mul_f32 v[192:193], v[98:99], v[192:193]
	v_cvt_pk_bf16_f32 v206, v186, v187
	v_cvt_pk_bf16_f32 v207, v188, v189
	v_cvt_pk_bf16_f32 v208, v190, v191
	v_cvt_pk_bf16_f32 v209, v192, v193
	s_nop 0
	v_permlane16_swap_b32_e32 v202, v204
	v_permlane16_swap_b32_e32 v203, v205
	v_permlane16_swap_b32_e32 v206, v208
	v_permlane16_swap_b32_e32 v207, v209
	s_nop 0
	global_store_dwordx4 v[158:159], v[202:205], off nt
	global_store_dwordx4 v[158:159], v[206:209], off offset:256 nt
	v_lshl_add_u64 v[158:159], v[158:159], 0, s[16:17]
	v_mul_f32_e32 v186, 0xbfb8aa3b, v92
	v_mul_f32_e32 v187, 0xbfb8aa3b, v93
	v_mul_f32_e32 v188, 0xbfb8aa3b, v94
	v_mul_f32_e32 v189, 0xbfb8aa3b, v95
	v_mul_f32_e32 v190, 0xbfb8aa3b, v88
	v_mul_f32_e32 v191, 0xbfb8aa3b, v89
	v_mul_f32_e32 v192, 0xbfb8aa3b, v90
	v_mul_f32_e32 v193, 0xbfb8aa3b, v91
	v_exp_f32_e32 v186, v186
	v_exp_f32_e32 v187, v187
	v_exp_f32_e32 v188, v188
	v_exp_f32_e32 v189, v189
	v_exp_f32_e32 v190, v190
	v_exp_f32_e32 v191, v191
	v_exp_f32_e32 v192, v192
	v_exp_f32_e32 v193, v193
	v_add_f32_e32 v186, 1.0, v186
	v_add_f32_e32 v187, 1.0, v187
	v_add_f32_e32 v188, 1.0, v188
	v_add_f32_e32 v189, 1.0, v189
	v_add_f32_e32 v190, 1.0, v190
	v_add_f32_e32 v191, 1.0, v191
	v_add_f32_e32 v192, 1.0, v192
	v_add_f32_e32 v193, 1.0, v193
	v_rcp_f32_e32 v186, v186
	v_rcp_f32_e32 v187, v187
	v_rcp_f32_e32 v188, v188
	v_rcp_f32_e32 v189, v189
	v_rcp_f32_e32 v190, v190
	v_rcp_f32_e32 v191, v191
	v_rcp_f32_e32 v192, v192
	v_rcp_f32_e32 v193, v193
	v_pk_mul_f32 v[186:187], v[92:93], v[186:187]
	v_pk_mul_f32 v[188:189], v[94:95], v[188:189]
	v_pk_mul_f32 v[190:191], v[88:89], v[190:191]
	v_pk_mul_f32 v[192:193], v[90:91], v[192:193]
	v_cvt_pk_bf16_f32 v194, v186, v187
	v_cvt_pk_bf16_f32 v195, v188, v189
	v_cvt_pk_bf16_f32 v196, v190, v191
	v_cvt_pk_bf16_f32 v197, v192, v193
	v_mul_f32_e32 v186, 0xbfb8aa3b, v84
	v_mul_f32_e32 v187, 0xbfb8aa3b, v85
	v_mul_f32_e32 v188, 0xbfb8aa3b, v86
	v_mul_f32_e32 v189, 0xbfb8aa3b, v87
	v_mul_f32_e32 v190, 0xbfb8aa3b, v80
	v_mul_f32_e32 v191, 0xbfb8aa3b, v81
	v_mul_f32_e32 v192, 0xbfb8aa3b, v82
	v_mul_f32_e32 v193, 0xbfb8aa3b, v83
	v_exp_f32_e32 v186, v186
	v_exp_f32_e32 v187, v187
	v_exp_f32_e32 v188, v188
	v_exp_f32_e32 v189, v189
	v_exp_f32_e32 v190, v190
	v_exp_f32_e32 v191, v191
	v_exp_f32_e32 v192, v192
	v_exp_f32_e32 v193, v193
	v_add_f32_e32 v186, 1.0, v186
	v_add_f32_e32 v187, 1.0, v187
	v_add_f32_e32 v188, 1.0, v188
	v_add_f32_e32 v189, 1.0, v189
	v_add_f32_e32 v190, 1.0, v190
	v_add_f32_e32 v191, 1.0, v191
	v_add_f32_e32 v192, 1.0, v192
	v_add_f32_e32 v193, 1.0, v193
	v_rcp_f32_e32 v186, v186
	v_rcp_f32_e32 v187, v187
	v_rcp_f32_e32 v188, v188
	v_rcp_f32_e32 v189, v189
	v_rcp_f32_e32 v190, v190
	v_rcp_f32_e32 v191, v191
	v_rcp_f32_e32 v192, v192
	v_rcp_f32_e32 v193, v193
	v_pk_mul_f32 v[186:187], v[84:85], v[186:187]
	v_pk_mul_f32 v[188:189], v[86:87], v[188:189]
	v_pk_mul_f32 v[190:191], v[80:81], v[190:191]
	v_pk_mul_f32 v[192:193], v[82:83], v[192:193]
	v_cvt_pk_bf16_f32 v198, v186, v187
	v_cvt_pk_bf16_f32 v199, v188, v189
	v_cvt_pk_bf16_f32 v200, v190, v191
	v_cvt_pk_bf16_f32 v201, v192, v193
	s_nop 0
	v_permlane16_swap_b32_e32 v194, v196
	v_permlane16_swap_b32_e32 v195, v197
	v_permlane16_swap_b32_e32 v198, v200
	v_permlane16_swap_b32_e32 v199, v201
	s_nop 0
	global_store_dwordx4 v[158:159], v[194:197], off nt
	global_store_dwordx4 v[158:159], v[198:201], off offset:256 nt
	v_lshl_add_u64 v[158:159], v[158:159], 0, s[16:17]
	v_mul_f32_e32 v186, 0xbfb8aa3b, v76
	v_mul_f32_e32 v187, 0xbfb8aa3b, v77
	v_mul_f32_e32 v188, 0xbfb8aa3b, v78
	v_mul_f32_e32 v189, 0xbfb8aa3b, v79
	v_mul_f32_e32 v190, 0xbfb8aa3b, v72
	v_mul_f32_e32 v191, 0xbfb8aa3b, v73
	v_mul_f32_e32 v192, 0xbfb8aa3b, v74
	v_mul_f32_e32 v193, 0xbfb8aa3b, v75
	v_exp_f32_e32 v186, v186
	v_exp_f32_e32 v187, v187
	v_exp_f32_e32 v188, v188
	v_exp_f32_e32 v189, v189
	v_exp_f32_e32 v190, v190
	v_exp_f32_e32 v191, v191
	v_exp_f32_e32 v192, v192
	v_exp_f32_e32 v193, v193
	v_add_f32_e32 v186, 1.0, v186
	v_add_f32_e32 v187, 1.0, v187
	v_add_f32_e32 v188, 1.0, v188
	v_add_f32_e32 v189, 1.0, v189
	v_add_f32_e32 v190, 1.0, v190
	v_add_f32_e32 v191, 1.0, v191
	v_add_f32_e32 v192, 1.0, v192
	v_add_f32_e32 v193, 1.0, v193
	v_rcp_f32_e32 v186, v186
	v_rcp_f32_e32 v187, v187
	v_rcp_f32_e32 v188, v188
	v_rcp_f32_e32 v189, v189
	v_rcp_f32_e32 v190, v190
	v_rcp_f32_e32 v191, v191
	v_rcp_f32_e32 v192, v192
	v_rcp_f32_e32 v193, v193
	v_pk_mul_f32 v[186:187], v[76:77], v[186:187]
	v_pk_mul_f32 v[188:189], v[78:79], v[188:189]
	v_pk_mul_f32 v[190:191], v[72:73], v[190:191]
	v_pk_mul_f32 v[192:193], v[74:75], v[192:193]
	v_cvt_pk_bf16_f32 v202, v186, v187
	v_cvt_pk_bf16_f32 v203, v188, v189
	v_cvt_pk_bf16_f32 v204, v190, v191
	v_cvt_pk_bf16_f32 v205, v192, v193
	v_mul_f32_e32 v186, 0xbfb8aa3b, v68
	v_mul_f32_e32 v187, 0xbfb8aa3b, v69
	v_mul_f32_e32 v188, 0xbfb8aa3b, v70
	v_mul_f32_e32 v189, 0xbfb8aa3b, v71
	v_mul_f32_e32 v190, 0xbfb8aa3b, v64
	v_mul_f32_e32 v191, 0xbfb8aa3b, v65
	v_mul_f32_e32 v192, 0xbfb8aa3b, v66
	v_mul_f32_e32 v193, 0xbfb8aa3b, v67
	v_exp_f32_e32 v186, v186
	v_exp_f32_e32 v187, v187
	v_exp_f32_e32 v188, v188
	v_exp_f32_e32 v189, v189
	v_exp_f32_e32 v190, v190
	v_exp_f32_e32 v191, v191
	v_exp_f32_e32 v192, v192
	v_exp_f32_e32 v193, v193
	v_add_f32_e32 v186, 1.0, v186
	v_add_f32_e32 v187, 1.0, v187
	v_add_f32_e32 v188, 1.0, v188
	v_add_f32_e32 v189, 1.0, v189
	v_add_f32_e32 v190, 1.0, v190
	v_add_f32_e32 v191, 1.0, v191
	v_add_f32_e32 v192, 1.0, v192
	v_add_f32_e32 v193, 1.0, v193
	v_rcp_f32_e32 v186, v186
	v_rcp_f32_e32 v187, v187
	v_rcp_f32_e32 v188, v188
	v_rcp_f32_e32 v189, v189
	v_rcp_f32_e32 v190, v190
	v_rcp_f32_e32 v191, v191
	v_rcp_f32_e32 v192, v192
	v_rcp_f32_e32 v193, v193
	v_pk_mul_f32 v[186:187], v[68:69], v[186:187]
	v_pk_mul_f32 v[188:189], v[70:71], v[188:189]
	v_pk_mul_f32 v[190:191], v[64:65], v[190:191]
	v_pk_mul_f32 v[192:193], v[66:67], v[192:193]
	v_cvt_pk_bf16_f32 v206, v186, v187
	v_cvt_pk_bf16_f32 v207, v188, v189
	v_cvt_pk_bf16_f32 v208, v190, v191
	v_cvt_pk_bf16_f32 v209, v192, v193
	s_nop 0
	v_permlane16_swap_b32_e32 v202, v204
	v_permlane16_swap_b32_e32 v203, v205
	v_permlane16_swap_b32_e32 v206, v208
	v_permlane16_swap_b32_e32 v207, v209
	s_nop 0
	global_store_dwordx4 v[158:159], v[202:205], off nt
	global_store_dwordx4 v[158:159], v[206:209], off offset:256 nt
	v_lshl_add_u64 v[158:159], v[158:159], 0, s[18:19]
	v_mul_f32_e32 v186, 0xbfb8aa3b, v60
	v_mul_f32_e32 v187, 0xbfb8aa3b, v61
	v_mul_f32_e32 v188, 0xbfb8aa3b, v62
	v_mul_f32_e32 v189, 0xbfb8aa3b, v63
	v_mul_f32_e32 v190, 0xbfb8aa3b, v56
	v_mul_f32_e32 v191, 0xbfb8aa3b, v57
	v_mul_f32_e32 v192, 0xbfb8aa3b, v58
	v_mul_f32_e32 v193, 0xbfb8aa3b, v59
	v_exp_f32_e32 v186, v186
	v_exp_f32_e32 v187, v187
	v_exp_f32_e32 v188, v188
	v_exp_f32_e32 v189, v189
	v_exp_f32_e32 v190, v190
	v_exp_f32_e32 v191, v191
	v_exp_f32_e32 v192, v192
	v_exp_f32_e32 v193, v193
	v_add_f32_e32 v186, 1.0, v186
	v_add_f32_e32 v187, 1.0, v187
	v_add_f32_e32 v188, 1.0, v188
	v_add_f32_e32 v189, 1.0, v189
	v_add_f32_e32 v190, 1.0, v190
	v_add_f32_e32 v191, 1.0, v191
	v_add_f32_e32 v192, 1.0, v192
	v_add_f32_e32 v193, 1.0, v193
	v_rcp_f32_e32 v186, v186
	v_rcp_f32_e32 v187, v187
	v_rcp_f32_e32 v188, v188
	v_rcp_f32_e32 v189, v189
	v_rcp_f32_e32 v190, v190
	v_rcp_f32_e32 v191, v191
	v_rcp_f32_e32 v192, v192
	v_rcp_f32_e32 v193, v193
	v_pk_mul_f32 v[186:187], v[60:61], v[186:187]
	v_pk_mul_f32 v[188:189], v[62:63], v[188:189]
	v_pk_mul_f32 v[190:191], v[56:57], v[190:191]
	v_pk_mul_f32 v[192:193], v[58:59], v[192:193]
	v_cvt_pk_bf16_f32 v194, v186, v187
	v_cvt_pk_bf16_f32 v195, v188, v189
	v_cvt_pk_bf16_f32 v196, v190, v191
	v_cvt_pk_bf16_f32 v197, v192, v193
	v_mul_f32_e32 v186, 0xbfb8aa3b, v52
	v_mul_f32_e32 v187, 0xbfb8aa3b, v53
	v_mul_f32_e32 v188, 0xbfb8aa3b, v54
	v_mul_f32_e32 v189, 0xbfb8aa3b, v55
	v_mul_f32_e32 v190, 0xbfb8aa3b, v48
	v_mul_f32_e32 v191, 0xbfb8aa3b, v49
	v_mul_f32_e32 v192, 0xbfb8aa3b, v50
	v_mul_f32_e32 v193, 0xbfb8aa3b, v51
	v_exp_f32_e32 v186, v186
	v_exp_f32_e32 v187, v187
	v_exp_f32_e32 v188, v188
	v_exp_f32_e32 v189, v189
	v_exp_f32_e32 v190, v190
	v_exp_f32_e32 v191, v191
	v_exp_f32_e32 v192, v192
	v_exp_f32_e32 v193, v193
	v_add_f32_e32 v186, 1.0, v186
	v_add_f32_e32 v187, 1.0, v187
	v_add_f32_e32 v188, 1.0, v188
	v_add_f32_e32 v189, 1.0, v189
	v_add_f32_e32 v190, 1.0, v190
	v_add_f32_e32 v191, 1.0, v191
	v_add_f32_e32 v192, 1.0, v192
	v_add_f32_e32 v193, 1.0, v193
	v_rcp_f32_e32 v186, v186
	v_rcp_f32_e32 v187, v187
	v_rcp_f32_e32 v188, v188
	v_rcp_f32_e32 v189, v189
	v_rcp_f32_e32 v190, v190
	v_rcp_f32_e32 v191, v191
	v_rcp_f32_e32 v192, v192
	v_rcp_f32_e32 v193, v193
	v_pk_mul_f32 v[186:187], v[52:53], v[186:187]
	v_pk_mul_f32 v[188:189], v[54:55], v[188:189]
	v_pk_mul_f32 v[190:191], v[48:49], v[190:191]
	v_pk_mul_f32 v[192:193], v[50:51], v[192:193]
	v_cvt_pk_bf16_f32 v198, v186, v187
	v_cvt_pk_bf16_f32 v199, v188, v189
	v_cvt_pk_bf16_f32 v200, v190, v191
	v_cvt_pk_bf16_f32 v201, v192, v193
	s_nop 0
	v_permlane16_swap_b32_e32 v194, v196
	v_permlane16_swap_b32_e32 v195, v197
	v_permlane16_swap_b32_e32 v198, v200
	v_permlane16_swap_b32_e32 v199, v201
	s_nop 0
	global_store_dwordx4 v[158:159], v[194:197], off nt
	global_store_dwordx4 v[158:159], v[198:201], off offset:256 nt
	v_lshl_add_u64 v[158:159], v[158:159], 0, s[16:17]
	v_mul_f32_e32 v186, 0xbfb8aa3b, v44
	v_mul_f32_e32 v187, 0xbfb8aa3b, v45
	v_mul_f32_e32 v188, 0xbfb8aa3b, v46
	v_mul_f32_e32 v189, 0xbfb8aa3b, v47
	v_mul_f32_e32 v190, 0xbfb8aa3b, v40
	v_mul_f32_e32 v191, 0xbfb8aa3b, v41
	v_mul_f32_e32 v192, 0xbfb8aa3b, v42
	v_mul_f32_e32 v193, 0xbfb8aa3b, v43
	v_exp_f32_e32 v186, v186
	v_exp_f32_e32 v187, v187
	v_exp_f32_e32 v188, v188
	v_exp_f32_e32 v189, v189
	v_exp_f32_e32 v190, v190
	v_exp_f32_e32 v191, v191
	v_exp_f32_e32 v192, v192
	v_exp_f32_e32 v193, v193
	v_add_f32_e32 v186, 1.0, v186
	v_add_f32_e32 v187, 1.0, v187
	v_add_f32_e32 v188, 1.0, v188
	v_add_f32_e32 v189, 1.0, v189
	v_add_f32_e32 v190, 1.0, v190
	v_add_f32_e32 v191, 1.0, v191
	v_add_f32_e32 v192, 1.0, v192
	v_add_f32_e32 v193, 1.0, v193
	v_rcp_f32_e32 v186, v186
	v_rcp_f32_e32 v187, v187
	v_rcp_f32_e32 v188, v188
	v_rcp_f32_e32 v189, v189
	v_rcp_f32_e32 v190, v190
	v_rcp_f32_e32 v191, v191
	v_rcp_f32_e32 v192, v192
	v_rcp_f32_e32 v193, v193
	v_pk_mul_f32 v[186:187], v[44:45], v[186:187]
	v_pk_mul_f32 v[188:189], v[46:47], v[188:189]
	v_pk_mul_f32 v[190:191], v[40:41], v[190:191]
	v_pk_mul_f32 v[192:193], v[42:43], v[192:193]
	v_cvt_pk_bf16_f32 v202, v186, v187
	v_cvt_pk_bf16_f32 v203, v188, v189
	v_cvt_pk_bf16_f32 v204, v190, v191
	v_cvt_pk_bf16_f32 v205, v192, v193
	v_mul_f32_e32 v186, 0xbfb8aa3b, v36
	v_mul_f32_e32 v187, 0xbfb8aa3b, v37
	v_mul_f32_e32 v188, 0xbfb8aa3b, v38
	v_mul_f32_e32 v189, 0xbfb8aa3b, v39
	v_mul_f32_e32 v190, 0xbfb8aa3b, v32
	v_mul_f32_e32 v191, 0xbfb8aa3b, v33
	v_mul_f32_e32 v192, 0xbfb8aa3b, v34
	v_mul_f32_e32 v193, 0xbfb8aa3b, v35
	v_exp_f32_e32 v186, v186
	v_exp_f32_e32 v187, v187
	v_exp_f32_e32 v188, v188
	v_exp_f32_e32 v189, v189
	v_exp_f32_e32 v190, v190
	v_exp_f32_e32 v191, v191
	v_exp_f32_e32 v192, v192
	v_exp_f32_e32 v193, v193
	v_add_f32_e32 v186, 1.0, v186
	v_add_f32_e32 v187, 1.0, v187
	v_add_f32_e32 v188, 1.0, v188
	v_add_f32_e32 v189, 1.0, v189
	v_add_f32_e32 v190, 1.0, v190
	v_add_f32_e32 v191, 1.0, v191
	v_add_f32_e32 v192, 1.0, v192
	v_add_f32_e32 v193, 1.0, v193
	v_rcp_f32_e32 v186, v186
	v_rcp_f32_e32 v187, v187
	v_rcp_f32_e32 v188, v188
	v_rcp_f32_e32 v189, v189
	v_rcp_f32_e32 v190, v190
	v_rcp_f32_e32 v191, v191
	v_rcp_f32_e32 v192, v192
	v_rcp_f32_e32 v193, v193
	v_pk_mul_f32 v[186:187], v[36:37], v[186:187]
	v_pk_mul_f32 v[188:189], v[38:39], v[188:189]
	v_pk_mul_f32 v[190:191], v[32:33], v[190:191]
	v_pk_mul_f32 v[192:193], v[34:35], v[192:193]
	v_cvt_pk_bf16_f32 v206, v186, v187
	v_cvt_pk_bf16_f32 v207, v188, v189
	v_cvt_pk_bf16_f32 v208, v190, v191
	v_cvt_pk_bf16_f32 v209, v192, v193
	s_nop 0
	v_permlane16_swap_b32_e32 v202, v204
	v_permlane16_swap_b32_e32 v203, v205
	v_permlane16_swap_b32_e32 v206, v208
	v_permlane16_swap_b32_e32 v207, v209
	s_nop 0
	global_store_dwordx4 v[158:159], v[202:205], off nt
	global_store_dwordx4 v[158:159], v[206:209], off offset:256 nt
	v_lshl_add_u64 v[158:159], v[158:159], 0, s[16:17]
	v_mul_f32_e32 v186, 0xbfb8aa3b, v28
	v_mul_f32_e32 v187, 0xbfb8aa3b, v29
	v_mul_f32_e32 v188, 0xbfb8aa3b, v30
	v_mul_f32_e32 v189, 0xbfb8aa3b, v31
	v_mul_f32_e32 v190, 0xbfb8aa3b, v24
	v_mul_f32_e32 v191, 0xbfb8aa3b, v25
	v_mul_f32_e32 v192, 0xbfb8aa3b, v26
	v_mul_f32_e32 v193, 0xbfb8aa3b, v27
	v_exp_f32_e32 v186, v186
	v_exp_f32_e32 v187, v187
	v_exp_f32_e32 v188, v188
	v_exp_f32_e32 v189, v189
	v_exp_f32_e32 v190, v190
	v_exp_f32_e32 v191, v191
	v_exp_f32_e32 v192, v192
	v_exp_f32_e32 v193, v193
	v_add_f32_e32 v186, 1.0, v186
	v_add_f32_e32 v187, 1.0, v187
	v_add_f32_e32 v188, 1.0, v188
	v_add_f32_e32 v189, 1.0, v189
	v_add_f32_e32 v190, 1.0, v190
	v_add_f32_e32 v191, 1.0, v191
	v_add_f32_e32 v192, 1.0, v192
	v_add_f32_e32 v193, 1.0, v193
	v_rcp_f32_e32 v186, v186
	v_rcp_f32_e32 v187, v187
	v_rcp_f32_e32 v188, v188
	v_rcp_f32_e32 v189, v189
	v_rcp_f32_e32 v190, v190
	v_rcp_f32_e32 v191, v191
	v_rcp_f32_e32 v192, v192
	v_rcp_f32_e32 v193, v193
	v_pk_mul_f32 v[186:187], v[28:29], v[186:187]
	v_pk_mul_f32 v[188:189], v[30:31], v[188:189]
	v_pk_mul_f32 v[190:191], v[24:25], v[190:191]
	v_pk_mul_f32 v[192:193], v[26:27], v[192:193]
	v_cvt_pk_bf16_f32 v194, v186, v187
	v_cvt_pk_bf16_f32 v195, v188, v189
	v_cvt_pk_bf16_f32 v196, v190, v191
	v_cvt_pk_bf16_f32 v197, v192, v193
	v_mul_f32_e32 v186, 0xbfb8aa3b, v20
	v_mul_f32_e32 v187, 0xbfb8aa3b, v21
	v_mul_f32_e32 v188, 0xbfb8aa3b, v22
	v_mul_f32_e32 v189, 0xbfb8aa3b, v23
	v_mul_f32_e32 v190, 0xbfb8aa3b, v16
	v_mul_f32_e32 v191, 0xbfb8aa3b, v17
	v_mul_f32_e32 v192, 0xbfb8aa3b, v18
	v_mul_f32_e32 v193, 0xbfb8aa3b, v19
	v_exp_f32_e32 v186, v186
	v_exp_f32_e32 v187, v187
	v_exp_f32_e32 v188, v188
	v_exp_f32_e32 v189, v189
	v_exp_f32_e32 v190, v190
	v_exp_f32_e32 v191, v191
	v_exp_f32_e32 v192, v192
	v_exp_f32_e32 v193, v193
	v_add_f32_e32 v186, 1.0, v186
	v_add_f32_e32 v187, 1.0, v187
	v_add_f32_e32 v188, 1.0, v188
	v_add_f32_e32 v189, 1.0, v189
	v_add_f32_e32 v190, 1.0, v190
	v_add_f32_e32 v191, 1.0, v191
	v_add_f32_e32 v192, 1.0, v192
	v_add_f32_e32 v193, 1.0, v193
	v_rcp_f32_e32 v186, v186
	v_rcp_f32_e32 v187, v187
	v_rcp_f32_e32 v188, v188
	v_rcp_f32_e32 v189, v189
	v_rcp_f32_e32 v190, v190
	v_rcp_f32_e32 v191, v191
	v_rcp_f32_e32 v192, v192
	v_rcp_f32_e32 v193, v193
	v_pk_mul_f32 v[186:187], v[20:21], v[186:187]
	v_pk_mul_f32 v[188:189], v[22:23], v[188:189]
	v_pk_mul_f32 v[190:191], v[16:17], v[190:191]
	v_pk_mul_f32 v[192:193], v[18:19], v[192:193]
	v_cvt_pk_bf16_f32 v198, v186, v187
	v_cvt_pk_bf16_f32 v199, v188, v189
	v_cvt_pk_bf16_f32 v200, v190, v191
	v_cvt_pk_bf16_f32 v201, v192, v193
	s_nop 0
	v_permlane16_swap_b32_e32 v194, v196
	v_permlane16_swap_b32_e32 v195, v197
	v_permlane16_swap_b32_e32 v198, v200
	v_permlane16_swap_b32_e32 v199, v201
	s_nop 0
	global_store_dwordx4 v[158:159], v[194:197], off nt
	global_store_dwordx4 v[158:159], v[198:201], off offset:256 nt
	v_lshl_add_u64 v[158:159], v[158:159], 0, s[16:17]
	v_mul_f32_e32 v186, 0xbfb8aa3b, v12
	v_mul_f32_e32 v187, 0xbfb8aa3b, v13
	v_mul_f32_e32 v188, 0xbfb8aa3b, v14
	v_mul_f32_e32 v189, 0xbfb8aa3b, v15
	v_mul_f32_e32 v190, 0xbfb8aa3b, v8
	v_mul_f32_e32 v191, 0xbfb8aa3b, v9
	v_mul_f32_e32 v192, 0xbfb8aa3b, v10
	v_mul_f32_e32 v193, 0xbfb8aa3b, v11
	v_exp_f32_e32 v186, v186
	v_exp_f32_e32 v187, v187
	v_exp_f32_e32 v188, v188
	v_exp_f32_e32 v189, v189
	v_exp_f32_e32 v190, v190
	v_exp_f32_e32 v191, v191
	v_exp_f32_e32 v192, v192
	v_exp_f32_e32 v193, v193
	v_add_f32_e32 v186, 1.0, v186
	v_add_f32_e32 v187, 1.0, v187
	v_add_f32_e32 v188, 1.0, v188
	v_add_f32_e32 v189, 1.0, v189
	v_add_f32_e32 v190, 1.0, v190
	v_add_f32_e32 v191, 1.0, v191
	v_add_f32_e32 v192, 1.0, v192
	v_add_f32_e32 v193, 1.0, v193
	v_rcp_f32_e32 v186, v186
	v_rcp_f32_e32 v187, v187
	v_rcp_f32_e32 v188, v188
	v_rcp_f32_e32 v189, v189
	v_rcp_f32_e32 v190, v190
	v_rcp_f32_e32 v191, v191
	v_rcp_f32_e32 v192, v192
	v_rcp_f32_e32 v193, v193
	v_pk_mul_f32 v[186:187], v[12:13], v[186:187]
	v_pk_mul_f32 v[188:189], v[14:15], v[188:189]
	v_pk_mul_f32 v[190:191], v[8:9], v[190:191]
	v_pk_mul_f32 v[192:193], v[10:11], v[192:193]
	v_cvt_pk_bf16_f32 v202, v186, v187
	v_cvt_pk_bf16_f32 v203, v188, v189
	v_cvt_pk_bf16_f32 v204, v190, v191
	v_cvt_pk_bf16_f32 v205, v192, v193
	v_mul_f32_e32 v186, 0xbfb8aa3b, v4
	v_mul_f32_e32 v187, 0xbfb8aa3b, v5
	v_mul_f32_e32 v188, 0xbfb8aa3b, v6
	v_mul_f32_e32 v189, 0xbfb8aa3b, v7
	v_mul_f32_e32 v190, 0xbfb8aa3b, v0
	v_mul_f32_e32 v191, 0xbfb8aa3b, v1
	v_mul_f32_e32 v192, 0xbfb8aa3b, v2
	v_mul_f32_e32 v193, 0xbfb8aa3b, v3
	v_exp_f32_e32 v186, v186
	v_exp_f32_e32 v187, v187
	v_exp_f32_e32 v188, v188
	v_exp_f32_e32 v189, v189
	v_exp_f32_e32 v190, v190
	v_exp_f32_e32 v191, v191
	v_exp_f32_e32 v192, v192
	v_exp_f32_e32 v193, v193
	v_add_f32_e32 v186, 1.0, v186
	v_add_f32_e32 v187, 1.0, v187
	v_add_f32_e32 v188, 1.0, v188
	v_add_f32_e32 v189, 1.0, v189
	v_add_f32_e32 v190, 1.0, v190
	v_add_f32_e32 v191, 1.0, v191
	v_add_f32_e32 v192, 1.0, v192
	v_add_f32_e32 v193, 1.0, v193
	v_rcp_f32_e32 v186, v186
	v_rcp_f32_e32 v187, v187
	v_rcp_f32_e32 v188, v188
	v_rcp_f32_e32 v189, v189
	v_rcp_f32_e32 v190, v190
	v_rcp_f32_e32 v191, v191
	v_rcp_f32_e32 v192, v192
	v_rcp_f32_e32 v193, v193
	v_pk_mul_f32 v[186:187], v[4:5], v[186:187]
	v_pk_mul_f32 v[188:189], v[6:7], v[188:189]
	v_pk_mul_f32 v[190:191], v[0:1], v[190:191]
	v_pk_mul_f32 v[192:193], v[2:3], v[192:193]
	v_cvt_pk_bf16_f32 v206, v186, v187
	v_cvt_pk_bf16_f32 v207, v188, v189
	v_cvt_pk_bf16_f32 v208, v190, v191
	v_cvt_pk_bf16_f32 v209, v192, v193
	s_nop 0
	v_permlane16_swap_b32_e32 v202, v204
	v_permlane16_swap_b32_e32 v203, v205
	v_permlane16_swap_b32_e32 v206, v208
	v_permlane16_swap_b32_e32 v207, v209
	s_nop 0
	global_store_dwordx4 v[158:159], v[202:205], off nt
	global_store_dwordx4 v[158:159], v[206:209], off offset:256 nt
	s_branch .LBB0_224
.Lepi_hg_forget:
	s_and_b32 s4, s2, 3
	s_lshl_b32 s4, s4, 8
	v_or_b32_e32 v160, s4, v166
	v_lshlrev_b32_e32 v160, 2, v160
	global_load_dwordx4 v[210:213], v160, s[98:99]
	global_load_dwordx4 v[214:217], v160, s[98:99] offset:64
	global_load_dwordx4 v[218:221], v160, s[98:99] offset:512
	global_load_dwordx4 v[222:225], v160, s[98:99] offset:576
	s_waitcnt vmcnt(0)
	v_mul_f32_e32 v186, 0x3fb8aa3b, v124
	v_mul_f32_e32 v187, 0x3fb8aa3b, v125
	v_mul_f32_e32 v188, 0x3fb8aa3b, v126
	v_mul_f32_e32 v189, 0x3fb8aa3b, v127
	v_mul_f32_e32 v190, 0x3fb8aa3b, v120
	v_mul_f32_e32 v191, 0x3fb8aa3b, v121
	v_mul_f32_e32 v192, 0x3fb8aa3b, v122
	v_mul_f32_e32 v193, 0x3fb8aa3b, v123
	v_exp_f32_e32 v186, v186
	v_exp_f32_e32 v187, v187
	v_exp_f32_e32 v188, v188
	v_exp_f32_e32 v189, v189
	v_exp_f32_e32 v190, v190
	v_exp_f32_e32 v191, v191
	v_exp_f32_e32 v192, v192
	v_exp_f32_e32 v193, v193
	v_add_f32_e32 v186, 1.0, v186
	v_add_f32_e32 v187, 1.0, v187
	v_add_f32_e32 v188, 1.0, v188
	v_add_f32_e32 v189, 1.0, v189
	v_add_f32_e32 v190, 1.0, v190
	v_add_f32_e32 v191, 1.0, v191
	v_add_f32_e32 v192, 1.0, v192
	v_add_f32_e32 v193, 1.0, v193
	v_rcp_f32_e32 v186, v186
	v_rcp_f32_e32 v187, v187
	v_rcp_f32_e32 v188, v188
	v_rcp_f32_e32 v189, v189
	v_rcp_f32_e32 v190, v190
	v_rcp_f32_e32 v191, v191
	v_rcp_f32_e32 v192, v192
	v_rcp_f32_e32 v193, v193
	v_pk_mul_f32 v[186:187], v[186:187], v[210:211]
	v_pk_mul_f32 v[188:189], v[188:189], v[212:213]
	v_pk_mul_f32 v[190:191], v[190:191], v[214:215]
	v_pk_mul_f32 v[192:193], v[192:193], v[216:217]
	v_cvt_pk_bf16_f32 v194, v186, v187
	v_cvt_pk_bf16_f32 v195, v188, v189
	v_cvt_pk_bf16_f32 v196, v190, v191
	v_cvt_pk_bf16_f32 v197, v192, v193
	v_mul_f32_e32 v186, 0x3fb8aa3b, v116
	v_mul_f32_e32 v187, 0x3fb8aa3b, v117
	v_mul_f32_e32 v188, 0x3fb8aa3b, v118
	v_mul_f32_e32 v189, 0x3fb8aa3b, v119
	v_mul_f32_e32 v190, 0x3fb8aa3b, v112
	v_mul_f32_e32 v191, 0x3fb8aa3b, v113
	v_mul_f32_e32 v192, 0x3fb8aa3b, v114
	v_mul_f32_e32 v193, 0x3fb8aa3b, v115
	v_exp_f32_e32 v186, v186
	v_exp_f32_e32 v187, v187
	v_exp_f32_e32 v188, v188
	v_exp_f32_e32 v189, v189
	v_exp_f32_e32 v190, v190
	v_exp_f32_e32 v191, v191
	v_exp_f32_e32 v192, v192
	v_exp_f32_e32 v193, v193
	v_add_f32_e32 v186, 1.0, v186
	v_add_f32_e32 v187, 1.0, v187
	v_add_f32_e32 v188, 1.0, v188
	v_add_f32_e32 v189, 1.0, v189
	v_add_f32_e32 v190, 1.0, v190
	v_add_f32_e32 v191, 1.0, v191
	v_add_f32_e32 v192, 1.0, v192
	v_add_f32_e32 v193, 1.0, v193
	v_rcp_f32_e32 v186, v186
	v_rcp_f32_e32 v187, v187
	v_rcp_f32_e32 v188, v188
	v_rcp_f32_e32 v189, v189
	v_rcp_f32_e32 v190, v190
	v_rcp_f32_e32 v191, v191
	v_rcp_f32_e32 v192, v192
	v_rcp_f32_e32 v193, v193
	v_pk_mul_f32 v[186:187], v[186:187], v[218:219]
	v_pk_mul_f32 v[188:189], v[188:189], v[220:221]
	v_pk_mul_f32 v[190:191], v[190:191], v[222:223]
	v_pk_mul_f32 v[192:193], v[192:193], v[224:225]
	v_cvt_pk_bf16_f32 v198, v186, v187
	v_cvt_pk_bf16_f32 v199, v188, v189
	v_cvt_pk_bf16_f32 v200, v190, v191
	v_cvt_pk_bf16_f32 v201, v192, v193
	s_nop 0
	v_permlane16_swap_b32_e32 v194, v196
	v_permlane16_swap_b32_e32 v195, v197
	v_permlane16_swap_b32_e32 v198, v200
	v_permlane16_swap_b32_e32 v199, v201
	s_nop 0
	global_store_dwordx4 v[158:159], v[194:197], off nt
	global_store_dwordx4 v[158:159], v[198:201], off offset:256 nt
	v_lshl_add_u64 v[158:159], v[158:159], 0, s[16:17]
	v_mul_f32_e32 v186, 0x3fb8aa3b, v108
	v_mul_f32_e32 v187, 0x3fb8aa3b, v109
	v_mul_f32_e32 v188, 0x3fb8aa3b, v110
	v_mul_f32_e32 v189, 0x3fb8aa3b, v111
	v_mul_f32_e32 v190, 0x3fb8aa3b, v104
	v_mul_f32_e32 v191, 0x3fb8aa3b, v105
	v_mul_f32_e32 v192, 0x3fb8aa3b, v106
	v_mul_f32_e32 v193, 0x3fb8aa3b, v107
	v_exp_f32_e32 v186, v186
	v_exp_f32_e32 v187, v187
	v_exp_f32_e32 v188, v188
	v_exp_f32_e32 v189, v189
	v_exp_f32_e32 v190, v190
	v_exp_f32_e32 v191, v191
	v_exp_f32_e32 v192, v192
	v_exp_f32_e32 v193, v193
	v_add_f32_e32 v186, 1.0, v186
	v_add_f32_e32 v187, 1.0, v187
	v_add_f32_e32 v188, 1.0, v188
	v_add_f32_e32 v189, 1.0, v189
	v_add_f32_e32 v190, 1.0, v190
	v_add_f32_e32 v191, 1.0, v191
	v_add_f32_e32 v192, 1.0, v192
	v_add_f32_e32 v193, 1.0, v193
	v_rcp_f32_e32 v186, v186
	v_rcp_f32_e32 v187, v187
	v_rcp_f32_e32 v188, v188
	v_rcp_f32_e32 v189, v189
	v_rcp_f32_e32 v190, v190
	v_rcp_f32_e32 v191, v191
	v_rcp_f32_e32 v192, v192
	v_rcp_f32_e32 v193, v193
	v_pk_mul_f32 v[186:187], v[186:187], v[210:211]
	v_pk_mul_f32 v[188:189], v[188:189], v[212:213]
	v_pk_mul_f32 v[190:191], v[190:191], v[214:215]
	v_pk_mul_f32 v[192:193], v[192:193], v[216:217]
	v_cvt_pk_bf16_f32 v202, v186, v187
	v_cvt_pk_bf16_f32 v203, v188, v189
	v_cvt_pk_bf16_f32 v204, v190, v191
	v_cvt_pk_bf16_f32 v205, v192, v193
	v_mul_f32_e32 v186, 0x3fb8aa3b, v100
	v_mul_f32_e32 v187, 0x3fb8aa3b, v101
	v_mul_f32_e32 v188, 0x3fb8aa3b, v102
	v_mul_f32_e32 v189, 0x3fb8aa3b, v103
	v_mul_f32_e32 v190, 0x3fb8aa3b, v96
	v_mul_f32_e32 v191, 0x3fb8aa3b, v97
	v_mul_f32_e32 v192, 0x3fb8aa3b, v98
	v_mul_f32_e32 v193, 0x3fb8aa3b, v99
	v_exp_f32_e32 v186, v186
	v_exp_f32_e32 v187, v187
	v_exp_f32_e32 v188, v188
	v_exp_f32_e32 v189, v189
	v_exp_f32_e32 v190, v190
	v_exp_f32_e32 v191, v191
	v_exp_f32_e32 v192, v192
	v_exp_f32_e32 v193, v193
	v_add_f32_e32 v186, 1.0, v186
	v_add_f32_e32 v187, 1.0, v187
	v_add_f32_e32 v188, 1.0, v188
	v_add_f32_e32 v189, 1.0, v189
	v_add_f32_e32 v190, 1.0, v190
	v_add_f32_e32 v191, 1.0, v191
	v_add_f32_e32 v192, 1.0, v192
	v_add_f32_e32 v193, 1.0, v193
	v_rcp_f32_e32 v186, v186
	v_rcp_f32_e32 v187, v187
	v_rcp_f32_e32 v188, v188
	v_rcp_f32_e32 v189, v189
	v_rcp_f32_e32 v190, v190
	v_rcp_f32_e32 v191, v191
	v_rcp_f32_e32 v192, v192
	v_rcp_f32_e32 v193, v193
	v_pk_mul_f32 v[186:187], v[186:187], v[218:219]
	v_pk_mul_f32 v[188:189], v[188:189], v[220:221]
	v_pk_mul_f32 v[190:191], v[190:191], v[222:223]
	v_pk_mul_f32 v[192:193], v[192:193], v[224:225]
	v_cvt_pk_bf16_f32 v206, v186, v187
	v_cvt_pk_bf16_f32 v207, v188, v189
	v_cvt_pk_bf16_f32 v208, v190, v191
	v_cvt_pk_bf16_f32 v209, v192, v193
	s_nop 0
	v_permlane16_swap_b32_e32 v202, v204
	v_permlane16_swap_b32_e32 v203, v205
	v_permlane16_swap_b32_e32 v206, v208
	v_permlane16_swap_b32_e32 v207, v209
	s_nop 0
	global_store_dwordx4 v[158:159], v[202:205], off nt
	global_store_dwordx4 v[158:159], v[206:209], off offset:256 nt
	v_lshl_add_u64 v[158:159], v[158:159], 0, s[16:17]
	v_mul_f32_e32 v186, 0x3fb8aa3b, v92
	v_mul_f32_e32 v187, 0x3fb8aa3b, v93
	v_mul_f32_e32 v188, 0x3fb8aa3b, v94
	v_mul_f32_e32 v189, 0x3fb8aa3b, v95
	v_mul_f32_e32 v190, 0x3fb8aa3b, v88
	v_mul_f32_e32 v191, 0x3fb8aa3b, v89
	v_mul_f32_e32 v192, 0x3fb8aa3b, v90
	v_mul_f32_e32 v193, 0x3fb8aa3b, v91
	v_exp_f32_e32 v186, v186
	v_exp_f32_e32 v187, v187
	v_exp_f32_e32 v188, v188
	v_exp_f32_e32 v189, v189
	v_exp_f32_e32 v190, v190
	v_exp_f32_e32 v191, v191
	v_exp_f32_e32 v192, v192
	v_exp_f32_e32 v193, v193
	v_add_f32_e32 v186, 1.0, v186
	v_add_f32_e32 v187, 1.0, v187
	v_add_f32_e32 v188, 1.0, v188
	v_add_f32_e32 v189, 1.0, v189
	v_add_f32_e32 v190, 1.0, v190
	v_add_f32_e32 v191, 1.0, v191
	v_add_f32_e32 v192, 1.0, v192
	v_add_f32_e32 v193, 1.0, v193
	v_rcp_f32_e32 v186, v186
	v_rcp_f32_e32 v187, v187
	v_rcp_f32_e32 v188, v188
	v_rcp_f32_e32 v189, v189
	v_rcp_f32_e32 v190, v190
	v_rcp_f32_e32 v191, v191
	v_rcp_f32_e32 v192, v192
	v_rcp_f32_e32 v193, v193
	v_pk_mul_f32 v[186:187], v[186:187], v[210:211]
	v_pk_mul_f32 v[188:189], v[188:189], v[212:213]
	v_pk_mul_f32 v[190:191], v[190:191], v[214:215]
	v_pk_mul_f32 v[192:193], v[192:193], v[216:217]
	v_cvt_pk_bf16_f32 v194, v186, v187
	v_cvt_pk_bf16_f32 v195, v188, v189
	v_cvt_pk_bf16_f32 v196, v190, v191
	v_cvt_pk_bf16_f32 v197, v192, v193
	v_mul_f32_e32 v186, 0x3fb8aa3b, v84
	v_mul_f32_e32 v187, 0x3fb8aa3b, v85
	v_mul_f32_e32 v188, 0x3fb8aa3b, v86
	v_mul_f32_e32 v189, 0x3fb8aa3b, v87
	v_mul_f32_e32 v190, 0x3fb8aa3b, v80
	v_mul_f32_e32 v191, 0x3fb8aa3b, v81
	v_mul_f32_e32 v192, 0x3fb8aa3b, v82
	v_mul_f32_e32 v193, 0x3fb8aa3b, v83
	v_exp_f32_e32 v186, v186
	v_exp_f32_e32 v187, v187
	v_exp_f32_e32 v188, v188
	v_exp_f32_e32 v189, v189
	v_exp_f32_e32 v190, v190
	v_exp_f32_e32 v191, v191
	v_exp_f32_e32 v192, v192
	v_exp_f32_e32 v193, v193
	v_add_f32_e32 v186, 1.0, v186
	v_add_f32_e32 v187, 1.0, v187
	v_add_f32_e32 v188, 1.0, v188
	v_add_f32_e32 v189, 1.0, v189
	v_add_f32_e32 v190, 1.0, v190
	v_add_f32_e32 v191, 1.0, v191
	v_add_f32_e32 v192, 1.0, v192
	v_add_f32_e32 v193, 1.0, v193
	v_rcp_f32_e32 v186, v186
	v_rcp_f32_e32 v187, v187
	v_rcp_f32_e32 v188, v188
	v_rcp_f32_e32 v189, v189
	v_rcp_f32_e32 v190, v190
	v_rcp_f32_e32 v191, v191
	v_rcp_f32_e32 v192, v192
	v_rcp_f32_e32 v193, v193
	v_pk_mul_f32 v[186:187], v[186:187], v[218:219]
	v_pk_mul_f32 v[188:189], v[188:189], v[220:221]
	v_pk_mul_f32 v[190:191], v[190:191], v[222:223]
	v_pk_mul_f32 v[192:193], v[192:193], v[224:225]
	v_cvt_pk_bf16_f32 v198, v186, v187
	v_cvt_pk_bf16_f32 v199, v188, v189
	v_cvt_pk_bf16_f32 v200, v190, v191
	v_cvt_pk_bf16_f32 v201, v192, v193
	s_nop 0
	v_permlane16_swap_b32_e32 v194, v196
	v_permlane16_swap_b32_e32 v195, v197
	v_permlane16_swap_b32_e32 v198, v200
	v_permlane16_swap_b32_e32 v199, v201
	s_nop 0
	global_store_dwordx4 v[158:159], v[194:197], off nt
	global_store_dwordx4 v[158:159], v[198:201], off offset:256 nt
	v_lshl_add_u64 v[158:159], v[158:159], 0, s[16:17]
	v_mul_f32_e32 v186, 0x3fb8aa3b, v76
	v_mul_f32_e32 v187, 0x3fb8aa3b, v77
	v_mul_f32_e32 v188, 0x3fb8aa3b, v78
	v_mul_f32_e32 v189, 0x3fb8aa3b, v79
	v_mul_f32_e32 v190, 0x3fb8aa3b, v72
	v_mul_f32_e32 v191, 0x3fb8aa3b, v73
	v_mul_f32_e32 v192, 0x3fb8aa3b, v74
	v_mul_f32_e32 v193, 0x3fb8aa3b, v75
	v_exp_f32_e32 v186, v186
	v_exp_f32_e32 v187, v187
	v_exp_f32_e32 v188, v188
	v_exp_f32_e32 v189, v189
	v_exp_f32_e32 v190, v190
	v_exp_f32_e32 v191, v191
	v_exp_f32_e32 v192, v192
	v_exp_f32_e32 v193, v193
	v_add_f32_e32 v186, 1.0, v186
	v_add_f32_e32 v187, 1.0, v187
	v_add_f32_e32 v188, 1.0, v188
	v_add_f32_e32 v189, 1.0, v189
	v_add_f32_e32 v190, 1.0, v190
	v_add_f32_e32 v191, 1.0, v191
	v_add_f32_e32 v192, 1.0, v192
	v_add_f32_e32 v193, 1.0, v193
	v_rcp_f32_e32 v186, v186
	v_rcp_f32_e32 v187, v187
	v_rcp_f32_e32 v188, v188
	v_rcp_f32_e32 v189, v189
	v_rcp_f32_e32 v190, v190
	v_rcp_f32_e32 v191, v191
	v_rcp_f32_e32 v192, v192
	v_rcp_f32_e32 v193, v193
	v_pk_mul_f32 v[186:187], v[186:187], v[210:211]
	v_pk_mul_f32 v[188:189], v[188:189], v[212:213]
	v_pk_mul_f32 v[190:191], v[190:191], v[214:215]
	v_pk_mul_f32 v[192:193], v[192:193], v[216:217]
	v_cvt_pk_bf16_f32 v202, v186, v187
	v_cvt_pk_bf16_f32 v203, v188, v189
	v_cvt_pk_bf16_f32 v204, v190, v191
	v_cvt_pk_bf16_f32 v205, v192, v193
	v_mul_f32_e32 v186, 0x3fb8aa3b, v68
	v_mul_f32_e32 v187, 0x3fb8aa3b, v69
	v_mul_f32_e32 v188, 0x3fb8aa3b, v70
	v_mul_f32_e32 v189, 0x3fb8aa3b, v71
	v_mul_f32_e32 v190, 0x3fb8aa3b, v64
	v_mul_f32_e32 v191, 0x3fb8aa3b, v65
	v_mul_f32_e32 v192, 0x3fb8aa3b, v66
	v_mul_f32_e32 v193, 0x3fb8aa3b, v67
	v_exp_f32_e32 v186, v186
	v_exp_f32_e32 v187, v187
	v_exp_f32_e32 v188, v188
	v_exp_f32_e32 v189, v189
	v_exp_f32_e32 v190, v190
	v_exp_f32_e32 v191, v191
	v_exp_f32_e32 v192, v192
	v_exp_f32_e32 v193, v193
	v_add_f32_e32 v186, 1.0, v186
	v_add_f32_e32 v187, 1.0, v187
	v_add_f32_e32 v188, 1.0, v188
	v_add_f32_e32 v189, 1.0, v189
	v_add_f32_e32 v190, 1.0, v190
	v_add_f32_e32 v191, 1.0, v191
	v_add_f32_e32 v192, 1.0, v192
	v_add_f32_e32 v193, 1.0, v193
	v_rcp_f32_e32 v186, v186
	v_rcp_f32_e32 v187, v187
	v_rcp_f32_e32 v188, v188
	v_rcp_f32_e32 v189, v189
	v_rcp_f32_e32 v190, v190
	v_rcp_f32_e32 v191, v191
	v_rcp_f32_e32 v192, v192
	v_rcp_f32_e32 v193, v193
	v_pk_mul_f32 v[186:187], v[186:187], v[218:219]
	v_pk_mul_f32 v[188:189], v[188:189], v[220:221]
	v_pk_mul_f32 v[190:191], v[190:191], v[222:223]
	v_pk_mul_f32 v[192:193], v[192:193], v[224:225]
	v_cvt_pk_bf16_f32 v206, v186, v187
	v_cvt_pk_bf16_f32 v207, v188, v189
	v_cvt_pk_bf16_f32 v208, v190, v191
	v_cvt_pk_bf16_f32 v209, v192, v193
	s_nop 0
	v_permlane16_swap_b32_e32 v202, v204
	v_permlane16_swap_b32_e32 v203, v205
	v_permlane16_swap_b32_e32 v206, v208
	v_permlane16_swap_b32_e32 v207, v209
	s_nop 0
	global_store_dwordx4 v[158:159], v[202:205], off nt
	global_store_dwordx4 v[158:159], v[206:209], off offset:256 nt
	v_lshl_add_u64 v[158:159], v[158:159], 0, s[18:19]
	v_mul_f32_e32 v186, 0x3fb8aa3b, v60
	v_mul_f32_e32 v187, 0x3fb8aa3b, v61
	v_mul_f32_e32 v188, 0x3fb8aa3b, v62
	v_mul_f32_e32 v189, 0x3fb8aa3b, v63
	v_mul_f32_e32 v190, 0x3fb8aa3b, v56
	v_mul_f32_e32 v191, 0x3fb8aa3b, v57
	v_mul_f32_e32 v192, 0x3fb8aa3b, v58
	v_mul_f32_e32 v193, 0x3fb8aa3b, v59
	v_exp_f32_e32 v186, v186
	v_exp_f32_e32 v187, v187
	v_exp_f32_e32 v188, v188
	v_exp_f32_e32 v189, v189
	v_exp_f32_e32 v190, v190
	v_exp_f32_e32 v191, v191
	v_exp_f32_e32 v192, v192
	v_exp_f32_e32 v193, v193
	v_add_f32_e32 v186, 1.0, v186
	v_add_f32_e32 v187, 1.0, v187
	v_add_f32_e32 v188, 1.0, v188
	v_add_f32_e32 v189, 1.0, v189
	v_add_f32_e32 v190, 1.0, v190
	v_add_f32_e32 v191, 1.0, v191
	v_add_f32_e32 v192, 1.0, v192
	v_add_f32_e32 v193, 1.0, v193
	v_rcp_f32_e32 v186, v186
	v_rcp_f32_e32 v187, v187
	v_rcp_f32_e32 v188, v188
	v_rcp_f32_e32 v189, v189
	v_rcp_f32_e32 v190, v190
	v_rcp_f32_e32 v191, v191
	v_rcp_f32_e32 v192, v192
	v_rcp_f32_e32 v193, v193
	v_pk_mul_f32 v[186:187], v[186:187], v[210:211]
	v_pk_mul_f32 v[188:189], v[188:189], v[212:213]
	v_pk_mul_f32 v[190:191], v[190:191], v[214:215]
	v_pk_mul_f32 v[192:193], v[192:193], v[216:217]
	v_cvt_pk_bf16_f32 v194, v186, v187
	v_cvt_pk_bf16_f32 v195, v188, v189
	v_cvt_pk_bf16_f32 v196, v190, v191
	v_cvt_pk_bf16_f32 v197, v192, v193
	v_mul_f32_e32 v186, 0x3fb8aa3b, v52
	v_mul_f32_e32 v187, 0x3fb8aa3b, v53
	v_mul_f32_e32 v188, 0x3fb8aa3b, v54
	v_mul_f32_e32 v189, 0x3fb8aa3b, v55
	v_mul_f32_e32 v190, 0x3fb8aa3b, v48
	v_mul_f32_e32 v191, 0x3fb8aa3b, v49
	v_mul_f32_e32 v192, 0x3fb8aa3b, v50
	v_mul_f32_e32 v193, 0x3fb8aa3b, v51
	v_exp_f32_e32 v186, v186
	v_exp_f32_e32 v187, v187
	v_exp_f32_e32 v188, v188
	v_exp_f32_e32 v189, v189
	v_exp_f32_e32 v190, v190
	v_exp_f32_e32 v191, v191
	v_exp_f32_e32 v192, v192
	v_exp_f32_e32 v193, v193
	v_add_f32_e32 v186, 1.0, v186
	v_add_f32_e32 v187, 1.0, v187
	v_add_f32_e32 v188, 1.0, v188
	v_add_f32_e32 v189, 1.0, v189
	v_add_f32_e32 v190, 1.0, v190
	v_add_f32_e32 v191, 1.0, v191
	v_add_f32_e32 v192, 1.0, v192
	v_add_f32_e32 v193, 1.0, v193
	v_rcp_f32_e32 v186, v186
	v_rcp_f32_e32 v187, v187
	v_rcp_f32_e32 v188, v188
	v_rcp_f32_e32 v189, v189
	v_rcp_f32_e32 v190, v190
	v_rcp_f32_e32 v191, v191
	v_rcp_f32_e32 v192, v192
	v_rcp_f32_e32 v193, v193
	v_pk_mul_f32 v[186:187], v[186:187], v[218:219]
	v_pk_mul_f32 v[188:189], v[188:189], v[220:221]
	v_pk_mul_f32 v[190:191], v[190:191], v[222:223]
	v_pk_mul_f32 v[192:193], v[192:193], v[224:225]
	v_cvt_pk_bf16_f32 v198, v186, v187
	v_cvt_pk_bf16_f32 v199, v188, v189
	v_cvt_pk_bf16_f32 v200, v190, v191
	v_cvt_pk_bf16_f32 v201, v192, v193
	s_nop 0
	v_permlane16_swap_b32_e32 v194, v196
	v_permlane16_swap_b32_e32 v195, v197
	v_permlane16_swap_b32_e32 v198, v200
	v_permlane16_swap_b32_e32 v199, v201
	s_nop 0
	global_store_dwordx4 v[158:159], v[194:197], off nt
	global_store_dwordx4 v[158:159], v[198:201], off offset:256 nt
	v_lshl_add_u64 v[158:159], v[158:159], 0, s[16:17]
	v_mul_f32_e32 v186, 0x3fb8aa3b, v44
	v_mul_f32_e32 v187, 0x3fb8aa3b, v45
	v_mul_f32_e32 v188, 0x3fb8aa3b, v46
	v_mul_f32_e32 v189, 0x3fb8aa3b, v47
	v_mul_f32_e32 v190, 0x3fb8aa3b, v40
	v_mul_f32_e32 v191, 0x3fb8aa3b, v41
	v_mul_f32_e32 v192, 0x3fb8aa3b, v42
	v_mul_f32_e32 v193, 0x3fb8aa3b, v43
	v_exp_f32_e32 v186, v186
	v_exp_f32_e32 v187, v187
	v_exp_f32_e32 v188, v188
	v_exp_f32_e32 v189, v189
	v_exp_f32_e32 v190, v190
	v_exp_f32_e32 v191, v191
	v_exp_f32_e32 v192, v192
	v_exp_f32_e32 v193, v193
	v_add_f32_e32 v186, 1.0, v186
	v_add_f32_e32 v187, 1.0, v187
	v_add_f32_e32 v188, 1.0, v188
	v_add_f32_e32 v189, 1.0, v189
	v_add_f32_e32 v190, 1.0, v190
	v_add_f32_e32 v191, 1.0, v191
	v_add_f32_e32 v192, 1.0, v192
	v_add_f32_e32 v193, 1.0, v193
	v_rcp_f32_e32 v186, v186
	v_rcp_f32_e32 v187, v187
	v_rcp_f32_e32 v188, v188
	v_rcp_f32_e32 v189, v189
	v_rcp_f32_e32 v190, v190
	v_rcp_f32_e32 v191, v191
	v_rcp_f32_e32 v192, v192
	v_rcp_f32_e32 v193, v193
	v_pk_mul_f32 v[186:187], v[186:187], v[210:211]
	v_pk_mul_f32 v[188:189], v[188:189], v[212:213]
	v_pk_mul_f32 v[190:191], v[190:191], v[214:215]
	v_pk_mul_f32 v[192:193], v[192:193], v[216:217]
	v_cvt_pk_bf16_f32 v202, v186, v187
	v_cvt_pk_bf16_f32 v203, v188, v189
	v_cvt_pk_bf16_f32 v204, v190, v191
	v_cvt_pk_bf16_f32 v205, v192, v193
	v_mul_f32_e32 v186, 0x3fb8aa3b, v36
	v_mul_f32_e32 v187, 0x3fb8aa3b, v37
	v_mul_f32_e32 v188, 0x3fb8aa3b, v38
	v_mul_f32_e32 v189, 0x3fb8aa3b, v39
	v_mul_f32_e32 v190, 0x3fb8aa3b, v32
	v_mul_f32_e32 v191, 0x3fb8aa3b, v33
	v_mul_f32_e32 v192, 0x3fb8aa3b, v34
	v_mul_f32_e32 v193, 0x3fb8aa3b, v35
	v_exp_f32_e32 v186, v186
	v_exp_f32_e32 v187, v187
	v_exp_f32_e32 v188, v188
	v_exp_f32_e32 v189, v189
	v_exp_f32_e32 v190, v190
	v_exp_f32_e32 v191, v191
	v_exp_f32_e32 v192, v192
	v_exp_f32_e32 v193, v193
	v_add_f32_e32 v186, 1.0, v186
	v_add_f32_e32 v187, 1.0, v187
	v_add_f32_e32 v188, 1.0, v188
	v_add_f32_e32 v189, 1.0, v189
	v_add_f32_e32 v190, 1.0, v190
	v_add_f32_e32 v191, 1.0, v191
	v_add_f32_e32 v192, 1.0, v192
	v_add_f32_e32 v193, 1.0, v193
	v_rcp_f32_e32 v186, v186
	v_rcp_f32_e32 v187, v187
	v_rcp_f32_e32 v188, v188
	v_rcp_f32_e32 v189, v189
	v_rcp_f32_e32 v190, v190
	v_rcp_f32_e32 v191, v191
	v_rcp_f32_e32 v192, v192
	v_rcp_f32_e32 v193, v193
	v_pk_mul_f32 v[186:187], v[186:187], v[218:219]
	v_pk_mul_f32 v[188:189], v[188:189], v[220:221]
	v_pk_mul_f32 v[190:191], v[190:191], v[222:223]
	v_pk_mul_f32 v[192:193], v[192:193], v[224:225]
	v_cvt_pk_bf16_f32 v206, v186, v187
	v_cvt_pk_bf16_f32 v207, v188, v189
	v_cvt_pk_bf16_f32 v208, v190, v191
	v_cvt_pk_bf16_f32 v209, v192, v193
	s_nop 0
	v_permlane16_swap_b32_e32 v202, v204
	v_permlane16_swap_b32_e32 v203, v205
	v_permlane16_swap_b32_e32 v206, v208
	v_permlane16_swap_b32_e32 v207, v209
	s_nop 0
	global_store_dwordx4 v[158:159], v[202:205], off nt
	global_store_dwordx4 v[158:159], v[206:209], off offset:256 nt
	v_lshl_add_u64 v[158:159], v[158:159], 0, s[16:17]
	v_mul_f32_e32 v186, 0x3fb8aa3b, v28
	v_mul_f32_e32 v187, 0x3fb8aa3b, v29
	v_mul_f32_e32 v188, 0x3fb8aa3b, v30
	v_mul_f32_e32 v189, 0x3fb8aa3b, v31
	v_mul_f32_e32 v190, 0x3fb8aa3b, v24
	v_mul_f32_e32 v191, 0x3fb8aa3b, v25
	v_mul_f32_e32 v192, 0x3fb8aa3b, v26
	v_mul_f32_e32 v193, 0x3fb8aa3b, v27
	v_exp_f32_e32 v186, v186
	v_exp_f32_e32 v187, v187
	v_exp_f32_e32 v188, v188
	v_exp_f32_e32 v189, v189
	v_exp_f32_e32 v190, v190
	v_exp_f32_e32 v191, v191
	v_exp_f32_e32 v192, v192
	v_exp_f32_e32 v193, v193
	v_add_f32_e32 v186, 1.0, v186
	v_add_f32_e32 v187, 1.0, v187
	v_add_f32_e32 v188, 1.0, v188
	v_add_f32_e32 v189, 1.0, v189
	v_add_f32_e32 v190, 1.0, v190
	v_add_f32_e32 v191, 1.0, v191
	v_add_f32_e32 v192, 1.0, v192
	v_add_f32_e32 v193, 1.0, v193
	v_rcp_f32_e32 v186, v186
	v_rcp_f32_e32 v187, v187
	v_rcp_f32_e32 v188, v188
	v_rcp_f32_e32 v189, v189
	v_rcp_f32_e32 v190, v190
	v_rcp_f32_e32 v191, v191
	v_rcp_f32_e32 v192, v192
	v_rcp_f32_e32 v193, v193
	v_pk_mul_f32 v[186:187], v[186:187], v[210:211]
	v_pk_mul_f32 v[188:189], v[188:189], v[212:213]
	v_pk_mul_f32 v[190:191], v[190:191], v[214:215]
	v_pk_mul_f32 v[192:193], v[192:193], v[216:217]
	v_cvt_pk_bf16_f32 v194, v186, v187
	v_cvt_pk_bf16_f32 v195, v188, v189
	v_cvt_pk_bf16_f32 v196, v190, v191
	v_cvt_pk_bf16_f32 v197, v192, v193
	v_mul_f32_e32 v186, 0x3fb8aa3b, v20
	v_mul_f32_e32 v187, 0x3fb8aa3b, v21
	v_mul_f32_e32 v188, 0x3fb8aa3b, v22
	v_mul_f32_e32 v189, 0x3fb8aa3b, v23
	v_mul_f32_e32 v190, 0x3fb8aa3b, v16
	v_mul_f32_e32 v191, 0x3fb8aa3b, v17
	v_mul_f32_e32 v192, 0x3fb8aa3b, v18
	v_mul_f32_e32 v193, 0x3fb8aa3b, v19
	v_exp_f32_e32 v186, v186
	v_exp_f32_e32 v187, v187
	v_exp_f32_e32 v188, v188
	v_exp_f32_e32 v189, v189
	v_exp_f32_e32 v190, v190
	v_exp_f32_e32 v191, v191
	v_exp_f32_e32 v192, v192
	v_exp_f32_e32 v193, v193
	v_add_f32_e32 v186, 1.0, v186
	v_add_f32_e32 v187, 1.0, v187
	v_add_f32_e32 v188, 1.0, v188
	v_add_f32_e32 v189, 1.0, v189
	v_add_f32_e32 v190, 1.0, v190
	v_add_f32_e32 v191, 1.0, v191
	v_add_f32_e32 v192, 1.0, v192
	v_add_f32_e32 v193, 1.0, v193
	v_rcp_f32_e32 v186, v186
	v_rcp_f32_e32 v187, v187
	v_rcp_f32_e32 v188, v188
	v_rcp_f32_e32 v189, v189
	v_rcp_f32_e32 v190, v190
	v_rcp_f32_e32 v191, v191
	v_rcp_f32_e32 v192, v192
	v_rcp_f32_e32 v193, v193
	v_pk_mul_f32 v[186:187], v[186:187], v[218:219]
	v_pk_mul_f32 v[188:189], v[188:189], v[220:221]
	v_pk_mul_f32 v[190:191], v[190:191], v[222:223]
	v_pk_mul_f32 v[192:193], v[192:193], v[224:225]
	v_cvt_pk_bf16_f32 v198, v186, v187
	v_cvt_pk_bf16_f32 v199, v188, v189
	v_cvt_pk_bf16_f32 v200, v190, v191
	v_cvt_pk_bf16_f32 v201, v192, v193
	s_nop 0
	v_permlane16_swap_b32_e32 v194, v196
	v_permlane16_swap_b32_e32 v195, v197
	v_permlane16_swap_b32_e32 v198, v200
	v_permlane16_swap_b32_e32 v199, v201
	s_nop 0
	global_store_dwordx4 v[158:159], v[194:197], off nt
	global_store_dwordx4 v[158:159], v[198:201], off offset:256 nt
	v_lshl_add_u64 v[158:159], v[158:159], 0, s[16:17]
	v_mul_f32_e32 v186, 0x3fb8aa3b, v12
	v_mul_f32_e32 v187, 0x3fb8aa3b, v13
	v_mul_f32_e32 v188, 0x3fb8aa3b, v14
	v_mul_f32_e32 v189, 0x3fb8aa3b, v15
	v_mul_f32_e32 v190, 0x3fb8aa3b, v8
	v_mul_f32_e32 v191, 0x3fb8aa3b, v9
	v_mul_f32_e32 v192, 0x3fb8aa3b, v10
	v_mul_f32_e32 v193, 0x3fb8aa3b, v11
	v_exp_f32_e32 v186, v186
	v_exp_f32_e32 v187, v187
	v_exp_f32_e32 v188, v188
	v_exp_f32_e32 v189, v189
	v_exp_f32_e32 v190, v190
	v_exp_f32_e32 v191, v191
	v_exp_f32_e32 v192, v192
	v_exp_f32_e32 v193, v193
	v_add_f32_e32 v186, 1.0, v186
	v_add_f32_e32 v187, 1.0, v187
	v_add_f32_e32 v188, 1.0, v188
	v_add_f32_e32 v189, 1.0, v189
	v_add_f32_e32 v190, 1.0, v190
	v_add_f32_e32 v191, 1.0, v191
	v_add_f32_e32 v192, 1.0, v192
	v_add_f32_e32 v193, 1.0, v193
	v_rcp_f32_e32 v186, v186
	v_rcp_f32_e32 v187, v187
	v_rcp_f32_e32 v188, v188
	v_rcp_f32_e32 v189, v189
	v_rcp_f32_e32 v190, v190
	v_rcp_f32_e32 v191, v191
	v_rcp_f32_e32 v192, v192
	v_rcp_f32_e32 v193, v193
	v_pk_mul_f32 v[186:187], v[186:187], v[210:211]
	v_pk_mul_f32 v[188:189], v[188:189], v[212:213]
	v_pk_mul_f32 v[190:191], v[190:191], v[214:215]
	v_pk_mul_f32 v[192:193], v[192:193], v[216:217]
	v_cvt_pk_bf16_f32 v202, v186, v187
	v_cvt_pk_bf16_f32 v203, v188, v189
	v_cvt_pk_bf16_f32 v204, v190, v191
	v_cvt_pk_bf16_f32 v205, v192, v193
	v_mul_f32_e32 v186, 0x3fb8aa3b, v4
	v_mul_f32_e32 v187, 0x3fb8aa3b, v5
	v_mul_f32_e32 v188, 0x3fb8aa3b, v6
	v_mul_f32_e32 v189, 0x3fb8aa3b, v7
	v_mul_f32_e32 v190, 0x3fb8aa3b, v0
	v_mul_f32_e32 v191, 0x3fb8aa3b, v1
	v_mul_f32_e32 v192, 0x3fb8aa3b, v2
	v_mul_f32_e32 v193, 0x3fb8aa3b, v3
	v_exp_f32_e32 v186, v186
	v_exp_f32_e32 v187, v187
	v_exp_f32_e32 v188, v188
	v_exp_f32_e32 v189, v189
	v_exp_f32_e32 v190, v190
	v_exp_f32_e32 v191, v191
	v_exp_f32_e32 v192, v192
	v_exp_f32_e32 v193, v193
	v_add_f32_e32 v186, 1.0, v186
	v_add_f32_e32 v187, 1.0, v187
	v_add_f32_e32 v188, 1.0, v188
	v_add_f32_e32 v189, 1.0, v189
	v_add_f32_e32 v190, 1.0, v190
	v_add_f32_e32 v191, 1.0, v191
	v_add_f32_e32 v192, 1.0, v192
	v_add_f32_e32 v193, 1.0, v193
	v_rcp_f32_e32 v186, v186
	v_rcp_f32_e32 v187, v187
	v_rcp_f32_e32 v188, v188
	v_rcp_f32_e32 v189, v189
	v_rcp_f32_e32 v190, v190
	v_rcp_f32_e32 v191, v191
	v_rcp_f32_e32 v192, v192
	v_rcp_f32_e32 v193, v193
	v_pk_mul_f32 v[186:187], v[186:187], v[218:219]
	v_pk_mul_f32 v[188:189], v[188:189], v[220:221]
	v_pk_mul_f32 v[190:191], v[190:191], v[222:223]
	v_pk_mul_f32 v[192:193], v[192:193], v[224:225]
	v_cvt_pk_bf16_f32 v206, v186, v187
	v_cvt_pk_bf16_f32 v207, v188, v189
	v_cvt_pk_bf16_f32 v208, v190, v191
	v_cvt_pk_bf16_f32 v209, v192, v193
	s_nop 0
	v_permlane16_swap_b32_e32 v202, v204
	v_permlane16_swap_b32_e32 v203, v205
	v_permlane16_swap_b32_e32 v206, v208
	v_permlane16_swap_b32_e32 v207, v209
	s_nop 0
	global_store_dwordx4 v[158:159], v[202:205], off nt
	global_store_dwordx4 v[158:159], v[206:209], off offset:256 nt
	s_branch .LBB0_224
.Lepi_hg_copy:
	v_cvt_pk_bf16_f32 v194, v124, v125
	v_cvt_pk_bf16_f32 v195, v126, v127
	v_cvt_pk_bf16_f32 v196, v120, v121
	v_cvt_pk_bf16_f32 v197, v122, v123
	v_cvt_pk_bf16_f32 v198, v116, v117
	v_cvt_pk_bf16_f32 v199, v118, v119
	v_cvt_pk_bf16_f32 v200, v112, v113
	v_cvt_pk_bf16_f32 v201, v114, v115
	s_nop 0
	v_permlane16_swap_b32_e32 v194, v196
	v_permlane16_swap_b32_e32 v195, v197
	v_permlane16_swap_b32_e32 v198, v200
	v_permlane16_swap_b32_e32 v199, v201
	s_nop 0
	global_store_dwordx4 v[158:159], v[194:197], off nt
	global_store_dwordx4 v[158:159], v[198:201], off offset:256 nt
	v_lshl_add_u64 v[158:159], v[158:159], 0, s[16:17]
	v_cvt_pk_bf16_f32 v202, v108, v109
	v_cvt_pk_bf16_f32 v203, v110, v111
	v_cvt_pk_bf16_f32 v204, v104, v105
	v_cvt_pk_bf16_f32 v205, v106, v107
	v_cvt_pk_bf16_f32 v206, v100, v101
	v_cvt_pk_bf16_f32 v207, v102, v103
	v_cvt_pk_bf16_f32 v208, v96, v97
	v_cvt_pk_bf16_f32 v209, v98, v99
	s_nop 0
	v_permlane16_swap_b32_e32 v202, v204
	v_permlane16_swap_b32_e32 v203, v205
	v_permlane16_swap_b32_e32 v206, v208
	v_permlane16_swap_b32_e32 v207, v209
	s_nop 0
	global_store_dwordx4 v[158:159], v[202:205], off nt
	global_store_dwordx4 v[158:159], v[206:209], off offset:256 nt
	v_lshl_add_u64 v[158:159], v[158:159], 0, s[16:17]
	v_cvt_pk_bf16_f32 v194, v92, v93
	v_cvt_pk_bf16_f32 v195, v94, v95
	v_cvt_pk_bf16_f32 v196, v88, v89
	v_cvt_pk_bf16_f32 v197, v90, v91
	v_cvt_pk_bf16_f32 v198, v84, v85
	v_cvt_pk_bf16_f32 v199, v86, v87
	v_cvt_pk_bf16_f32 v200, v80, v81
	v_cvt_pk_bf16_f32 v201, v82, v83
	s_nop 0
	v_permlane16_swap_b32_e32 v194, v196
	v_permlane16_swap_b32_e32 v195, v197
	v_permlane16_swap_b32_e32 v198, v200
	v_permlane16_swap_b32_e32 v199, v201
	s_nop 0
	global_store_dwordx4 v[158:159], v[194:197], off nt
	global_store_dwordx4 v[158:159], v[198:201], off offset:256 nt
	v_lshl_add_u64 v[158:159], v[158:159], 0, s[16:17]
	v_cvt_pk_bf16_f32 v202, v76, v77
	v_cvt_pk_bf16_f32 v203, v78, v79
	v_cvt_pk_bf16_f32 v204, v72, v73
	v_cvt_pk_bf16_f32 v205, v74, v75
	v_cvt_pk_bf16_f32 v206, v68, v69
	v_cvt_pk_bf16_f32 v207, v70, v71
	v_cvt_pk_bf16_f32 v208, v64, v65
	v_cvt_pk_bf16_f32 v209, v66, v67
	s_nop 0
	v_permlane16_swap_b32_e32 v202, v204
	v_permlane16_swap_b32_e32 v203, v205
	v_permlane16_swap_b32_e32 v206, v208
	v_permlane16_swap_b32_e32 v207, v209
	s_nop 0
	global_store_dwordx4 v[158:159], v[202:205], off nt
	global_store_dwordx4 v[158:159], v[206:209], off offset:256 nt
	v_lshl_add_u64 v[158:159], v[158:159], 0, s[18:19]
	v_cvt_pk_bf16_f32 v194, v60, v61
	v_cvt_pk_bf16_f32 v195, v62, v63
	v_cvt_pk_bf16_f32 v196, v56, v57
	v_cvt_pk_bf16_f32 v197, v58, v59
	v_cvt_pk_bf16_f32 v198, v52, v53
	v_cvt_pk_bf16_f32 v199, v54, v55
	v_cvt_pk_bf16_f32 v200, v48, v49
	v_cvt_pk_bf16_f32 v201, v50, v51
	s_nop 0
	v_permlane16_swap_b32_e32 v194, v196
	v_permlane16_swap_b32_e32 v195, v197
	v_permlane16_swap_b32_e32 v198, v200
	v_permlane16_swap_b32_e32 v199, v201
	s_nop 0
	global_store_dwordx4 v[158:159], v[194:197], off nt
	global_store_dwordx4 v[158:159], v[198:201], off offset:256 nt
	v_lshl_add_u64 v[158:159], v[158:159], 0, s[16:17]
	v_cvt_pk_bf16_f32 v202, v44, v45
	v_cvt_pk_bf16_f32 v203, v46, v47
	v_cvt_pk_bf16_f32 v204, v40, v41
	v_cvt_pk_bf16_f32 v205, v42, v43
	v_cvt_pk_bf16_f32 v206, v36, v37
	v_cvt_pk_bf16_f32 v207, v38, v39
	v_cvt_pk_bf16_f32 v208, v32, v33
	v_cvt_pk_bf16_f32 v209, v34, v35
	s_nop 0
	v_permlane16_swap_b32_e32 v202, v204
	v_permlane16_swap_b32_e32 v203, v205
	v_permlane16_swap_b32_e32 v206, v208
	v_permlane16_swap_b32_e32 v207, v209
	s_nop 0
	global_store_dwordx4 v[158:159], v[202:205], off nt
	global_store_dwordx4 v[158:159], v[206:209], off offset:256 nt
	v_lshl_add_u64 v[158:159], v[158:159], 0, s[16:17]
	v_cvt_pk_bf16_f32 v194, v28, v29
	v_cvt_pk_bf16_f32 v195, v30, v31
	v_cvt_pk_bf16_f32 v196, v24, v25
	v_cvt_pk_bf16_f32 v197, v26, v27
	v_cvt_pk_bf16_f32 v198, v20, v21
	v_cvt_pk_bf16_f32 v199, v22, v23
	v_cvt_pk_bf16_f32 v200, v16, v17
	v_cvt_pk_bf16_f32 v201, v18, v19
	s_nop 0
	v_permlane16_swap_b32_e32 v194, v196
	v_permlane16_swap_b32_e32 v195, v197
	v_permlane16_swap_b32_e32 v198, v200
	v_permlane16_swap_b32_e32 v199, v201
	s_nop 0
	global_store_dwordx4 v[158:159], v[194:197], off nt
	global_store_dwordx4 v[158:159], v[198:201], off offset:256 nt
	v_lshl_add_u64 v[158:159], v[158:159], 0, s[16:17]
	v_cvt_pk_bf16_f32 v202, v12, v13
	v_cvt_pk_bf16_f32 v203, v14, v15
	v_cvt_pk_bf16_f32 v204, v8, v9
	v_cvt_pk_bf16_f32 v205, v10, v11
	v_cvt_pk_bf16_f32 v206, v4, v5
	v_cvt_pk_bf16_f32 v207, v6, v7
	v_cvt_pk_bf16_f32 v208, v0, v1
	v_cvt_pk_bf16_f32 v209, v2, v3
	s_nop 0
	v_permlane16_swap_b32_e32 v202, v204
	v_permlane16_swap_b32_e32 v203, v205
	v_permlane16_swap_b32_e32 v206, v208
	v_permlane16_swap_b32_e32 v207, v209
	s_nop 0
	global_store_dwordx4 v[158:159], v[202:205], off nt
	global_store_dwordx4 v[158:159], v[206:209], off offset:256 nt
	s_branch .LBB0_224

.LBB0_737:
	ds_read_b128 v[146:149], v154
	ds_read_b128 v[170:173], v155
	ds_read_b128 v[174:177], v156
	ds_read_b128 v[178:181], v157
	s_add_u32 s18, s6, 0xfff7c080
	s_addc_u32 s19, s7, -1
	s_cmp_eq_u32 s52, 28
	s_cselect_b32 s21, s17, s19
	s_cselect_b32 s20, s16, s18
	s_cselect_b32 s19, s9, s39
	s_cselect_b32 s18, s8, s38
	s_mov_b32 m0, s46
	v_lshl_add_u64 v[150:151], s[6:7], 0, v[138:139]
	ds_read_b128 v[182:185], v152
	ds_read_b128 v[186:189], v152 offset:1024
	ds_read_b128 v[190:193], v152 offset:2048
	ds_read_b128 v[194:197], v152 offset:3072
	ds_read_b128 v[198:201], v152 offset:4096
	ds_read_b128 v[202:205], v152 offset:5120
	ds_read_b128 v[206:209], v152 offset:6144
	ds_read_b128 v[210:213], v152 offset:7168
	global_load_lds_dwordx4 v[150:151], off
	v_lshl_add_u64 v[150:151], s[6:7], 0, v[140:141]
	s_mov_b32 m0, s47
	s_nop 0
	global_load_lds_dwordx4 v[150:151], off
	s_waitcnt lgkmcnt(8)
	s_barrier
	s_waitcnt lgkmcnt(0)
	s_setprio 1
	s_waitcnt lgkmcnt(0)
	v_mfma_f32_16x16x32_bf16 v[124:127], v[146:149], v[182:185], v[124:127]
	v_mfma_f32_16x16x32_bf16 v[120:123], v[174:177], v[182:185], v[120:123]
	v_mfma_f32_16x16x32_bf16 v[108:111], v[146:149], v[190:193], v[108:111]
	v_mfma_f32_16x16x32_bf16 v[104:107], v[174:177], v[190:193], v[104:107]
	v_mfma_f32_16x16x32_bf16 v[92:95], v[146:149], v[198:201], v[92:95]
	v_mfma_f32_16x16x32_bf16 v[88:91], v[174:177], v[198:201], v[88:91]
	v_mfma_f32_16x16x32_bf16 v[76:79], v[146:149], v[206:209], v[76:79]
	v_mfma_f32_16x16x32_bf16 v[72:75], v[174:177], v[206:209], v[72:75]
	v_mfma_f32_16x16x32_bf16 v[124:127], v[170:173], v[186:189], v[124:127]
	v_mfma_f32_16x16x32_bf16 v[120:123], v[178:181], v[186:189], v[120:123]
	v_mfma_f32_16x16x32_bf16 v[108:111], v[170:173], v[194:197], v[108:111]
	v_mfma_f32_16x16x32_bf16 v[104:107], v[178:181], v[194:197], v[104:107]
	v_mfma_f32_16x16x32_bf16 v[92:95], v[170:173], v[202:205], v[92:95]
	v_mfma_f32_16x16x32_bf16 v[88:91], v[178:181], v[202:205], v[88:91]
	v_mfma_f32_16x16x32_bf16 v[76:79], v[170:173], v[210:213], v[76:79]
	v_mfma_f32_16x16x32_bf16 v[72:75], v[178:181], v[210:213], v[72:75]
	s_setprio 0
	s_barrier
	s_mov_b32 m0, s23
	v_lshl_add_u64 v[150:151], s[18:19], 0, v[130:131]
	ds_read_b128 v[214:217], v158
	ds_read_b128 v[218:221], v159
	ds_read_b128 v[222:225], v160
	ds_read_b128 v[226:229], v161
	global_load_lds_dwordx4 v[150:151], off
	v_lshl_add_u64 v[230:231], s[18:19], 0, v[132:133]
	s_mov_b32 m0, s24
	s_nop 0
	global_load_lds_dwordx4 v[230:231], off
	s_barrier
	s_waitcnt lgkmcnt(0)
	s_setprio 1
	s_waitcnt lgkmcnt(0)
	v_mfma_f32_16x16x32_bf16 v[116:119], v[214:217], v[182:185], v[116:119]
	v_mfma_f32_16x16x32_bf16 v[112:115], v[222:225], v[182:185], v[112:115]
	v_mfma_f32_16x16x32_bf16 v[100:103], v[214:217], v[190:193], v[100:103]
	v_mfma_f32_16x16x32_bf16 v[96:99], v[222:225], v[190:193], v[96:99]
	v_mfma_f32_16x16x32_bf16 v[84:87], v[214:217], v[198:201], v[84:87]
	v_mfma_f32_16x16x32_bf16 v[80:83], v[222:225], v[198:201], v[80:83]
	v_mfma_f32_16x16x32_bf16 v[68:71], v[214:217], v[206:209], v[68:71]
	v_mfma_f32_16x16x32_bf16 v[64:67], v[222:225], v[206:209], v[64:67]
	v_mfma_f32_16x16x32_bf16 v[116:119], v[218:221], v[186:189], v[116:119]
	v_mfma_f32_16x16x32_bf16 v[112:115], v[226:229], v[186:189], v[112:115]
	v_mfma_f32_16x16x32_bf16 v[100:103], v[218:221], v[194:197], v[100:103]
	v_mfma_f32_16x16x32_bf16 v[96:99], v[226:229], v[194:197], v[96:99]
	v_mfma_f32_16x16x32_bf16 v[84:87], v[218:221], v[202:205], v[84:87]
	v_mfma_f32_16x16x32_bf16 v[80:83], v[226:229], v[202:205], v[80:83]
	v_mfma_f32_16x16x32_bf16 v[68:71], v[218:221], v[210:213], v[68:71]
	v_mfma_f32_16x16x32_bf16 v[64:67], v[226:229], v[210:213], v[64:67]
	s_setprio 0
	s_mov_b32 m0, s22
	v_lshl_add_u64 v[232:233], s[20:21], 0, v[130:131]
	s_barrier
	ds_read_b128 v[182:185], v152 offset:16384
	ds_read_b128 v[186:189], v152 offset:17408
	ds_read_b128 v[190:193], v152 offset:18432
	ds_read_b128 v[194:197], v152 offset:19456
	ds_read_b128 v[198:201], v152 offset:20480
	ds_read_b128 v[202:205], v152 offset:21504
	ds_read_b128 v[206:209], v152 offset:22528
	ds_read_b128 v[210:213], v152 offset:23552
	global_load_lds_dwordx4 v[232:233], off
	v_lshl_add_u64 v[234:235], s[20:21], 0, v[132:133]
	s_mov_b32 m0, s25
	s_nop 0
	global_load_lds_dwordx4 v[234:235], off
	s_barrier
	s_waitcnt lgkmcnt(0)
	s_setprio 1
	s_waitcnt lgkmcnt(0)
	v_mfma_f32_16x16x32_bf16 v[60:63], v[146:149], v[182:185], v[60:63]
	v_mfma_f32_16x16x32_bf16 v[56:59], v[174:177], v[182:185], v[56:59]
	v_mfma_f32_16x16x32_bf16 v[44:47], v[146:149], v[190:193], v[44:47]
	v_mfma_f32_16x16x32_bf16 v[40:43], v[174:177], v[190:193], v[40:43]
	v_mfma_f32_16x16x32_bf16 v[28:31], v[146:149], v[198:201], v[28:31]
	v_mfma_f32_16x16x32_bf16 v[24:27], v[174:177], v[198:201], v[24:27]
	v_mfma_f32_16x16x32_bf16 v[12:15], v[146:149], v[206:209], v[12:15]
	v_mfma_f32_16x16x32_bf16 v[8:11], v[174:177], v[206:209], v[8:11]
	v_mfma_f32_16x16x32_bf16 v[60:63], v[170:173], v[186:189], v[60:63]
	v_mfma_f32_16x16x32_bf16 v[56:59], v[178:181], v[186:189], v[56:59]
	v_mfma_f32_16x16x32_bf16 v[44:47], v[170:173], v[194:197], v[44:47]
	v_mfma_f32_16x16x32_bf16 v[40:43], v[178:181], v[194:197], v[40:43]
	v_mfma_f32_16x16x32_bf16 v[28:31], v[170:173], v[202:205], v[28:31]
	v_mfma_f32_16x16x32_bf16 v[24:27], v[178:181], v[202:205], v[24:27]
	v_mfma_f32_16x16x32_bf16 v[12:15], v[170:173], v[210:213], v[12:15]
	v_mfma_f32_16x16x32_bf16 v[8:11], v[178:181], v[210:213], v[8:11]
	s_setprio 0
	s_barrier
	s_add_u32 s54, s18, 0x84000
	s_addc_u32 s55, s19, 0
	s_mov_b32 m0, s26
	v_lshl_add_u64 v[146:147], s[54:55], 0, v[130:131]
	global_load_lds_dwordx4 v[146:147], off
	v_lshl_add_u64 v[146:147], s[54:55], 0, v[132:133]
	s_mov_b32 m0, s27
	s_nop 0
	global_load_lds_dwordx4 v[146:147], off
	s_waitcnt vmcnt(6)
	s_barrier
	s_setprio 1
	v_mfma_f32_16x16x32_bf16 v[52:55], v[214:217], v[182:185], v[52:55]
	v_mfma_f32_16x16x32_bf16 v[48:51], v[222:225], v[182:185], v[48:51]
	v_mfma_f32_16x16x32_bf16 v[36:39], v[214:217], v[190:193], v[36:39]
	v_mfma_f32_16x16x32_bf16 v[32:35], v[222:225], v[190:193], v[32:35]
	v_mfma_f32_16x16x32_bf16 v[20:23], v[214:217], v[198:201], v[20:23]
	v_mfma_f32_16x16x32_bf16 v[16:19], v[222:225], v[198:201], v[16:19]
	v_mfma_f32_16x16x32_bf16 v[4:7], v[214:217], v[206:209], v[4:7]
	v_mfma_f32_16x16x32_bf16 v[0:3], v[222:225], v[206:209], v[0:3]
	v_mfma_f32_16x16x32_bf16 v[52:55], v[218:221], v[186:189], v[52:55]
	v_mfma_f32_16x16x32_bf16 v[48:51], v[226:229], v[186:189], v[48:51]
	v_mfma_f32_16x16x32_bf16 v[36:39], v[218:221], v[194:197], v[36:39]
	v_mfma_f32_16x16x32_bf16 v[32:35], v[226:229], v[194:197], v[32:35]
	v_mfma_f32_16x16x32_bf16 v[20:23], v[218:221], v[202:205], v[20:23]
	v_mfma_f32_16x16x32_bf16 v[16:19], v[226:229], v[202:205], v[16:19]
	v_mfma_f32_16x16x32_bf16 v[4:7], v[218:221], v[210:213], v[4:7]
	v_mfma_f32_16x16x32_bf16 v[0:3], v[226:229], v[210:213], v[0:3]
	s_setprio 0
	s_barrier
	ds_read_b128 v[146:149], v162
	ds_read_b128 v[170:173], v163
	ds_read_b128 v[174:177], v164
	ds_read_b128 v[178:181], v165
	s_add_u32 s20, s20, 0x84000
	s_addc_u32 s21, s21, 0
	s_mov_b32 m0, s28
	v_lshl_add_u64 v[214:215], s[20:21], 0, v[130:131]
	ds_read_b128 v[182:185], v152 offset:32768
	ds_read_b128 v[186:189], v152 offset:33792
	ds_read_b128 v[190:193], v152 offset:34816
	ds_read_b128 v[194:197], v152 offset:35840
	ds_read_b128 v[198:201], v152 offset:36864
	ds_read_b128 v[202:205], v152 offset:37888
	ds_read_b128 v[206:209], v152 offset:38912
	ds_read_b128 v[210:213], v152 offset:39936
	global_load_lds_dwordx4 v[214:215], off
	v_lshl_add_u64 v[214:215], s[20:21], 0, v[132:133]
	s_mov_b32 m0, s29
	s_nop 0
	global_load_lds_dwordx4 v[214:215], off
	s_waitcnt lgkmcnt(8)
	s_barrier
	s_waitcnt lgkmcnt(0)
	s_setprio 1
	s_waitcnt lgkmcnt(0)
	v_mfma_f32_16x16x32_bf16 v[124:127], v[146:149], v[182:185], v[124:127]
	v_mfma_f32_16x16x32_bf16 v[120:123], v[174:177], v[182:185], v[120:123]
	v_mfma_f32_16x16x32_bf16 v[108:111], v[146:149], v[190:193], v[108:111]
	v_mfma_f32_16x16x32_bf16 v[104:107], v[174:177], v[190:193], v[104:107]
	v_mfma_f32_16x16x32_bf16 v[92:95], v[146:149], v[198:201], v[92:95]
	v_mfma_f32_16x16x32_bf16 v[88:91], v[174:177], v[198:201], v[88:91]
	v_mfma_f32_16x16x32_bf16 v[76:79], v[146:149], v[206:209], v[76:79]
	v_mfma_f32_16x16x32_bf16 v[72:75], v[174:177], v[206:209], v[72:75]
	v_mfma_f32_16x16x32_bf16 v[124:127], v[170:173], v[186:189], v[124:127]
	v_mfma_f32_16x16x32_bf16 v[120:123], v[178:181], v[186:189], v[120:123]
	v_mfma_f32_16x16x32_bf16 v[108:111], v[170:173], v[194:197], v[108:111]
	v_mfma_f32_16x16x32_bf16 v[104:107], v[178:181], v[194:197], v[104:107]
	v_mfma_f32_16x16x32_bf16 v[92:95], v[170:173], v[202:205], v[92:95]
	v_mfma_f32_16x16x32_bf16 v[88:91], v[178:181], v[202:205], v[88:91]
	v_mfma_f32_16x16x32_bf16 v[76:79], v[170:173], v[210:213], v[76:79]
	v_mfma_f32_16x16x32_bf16 v[72:75], v[178:181], v[210:213], v[72:75]
	s_setprio 0
	s_barrier
	s_mov_b32 m0, s31
	v_lshl_add_u64 v[150:151], v[150:151], 0, s[12:13]
	ds_read_b128 v[214:217], v166
	ds_read_b128 v[218:221], v167
	ds_read_b128 v[222:225], v168
	ds_read_b128 v[226:229], v169
	global_load_lds_dwordx4 v[150:151], off
	v_lshl_add_u64 v[150:151], v[230:231], 0, s[12:13]
	s_mov_b32 m0, s33
	s_nop 0
	global_load_lds_dwordx4 v[150:151], off
	s_barrier
	s_waitcnt lgkmcnt(0)
	s_setprio 1
	s_waitcnt lgkmcnt(0)
	v_mfma_f32_16x16x32_bf16 v[116:119], v[214:217], v[182:185], v[116:119]
	v_mfma_f32_16x16x32_bf16 v[112:115], v[222:225], v[182:185], v[112:115]
	v_mfma_f32_16x16x32_bf16 v[100:103], v[214:217], v[190:193], v[100:103]
	v_mfma_f32_16x16x32_bf16 v[96:99], v[222:225], v[190:193], v[96:99]
	v_mfma_f32_16x16x32_bf16 v[84:87], v[214:217], v[198:201], v[84:87]
	v_mfma_f32_16x16x32_bf16 v[80:83], v[222:225], v[198:201], v[80:83]
	v_mfma_f32_16x16x32_bf16 v[68:71], v[214:217], v[206:209], v[68:71]
	v_mfma_f32_16x16x32_bf16 v[64:67], v[222:225], v[206:209], v[64:67]
	v_mfma_f32_16x16x32_bf16 v[116:119], v[218:221], v[186:189], v[116:119]
	v_mfma_f32_16x16x32_bf16 v[112:115], v[226:229], v[186:189], v[112:115]
	v_mfma_f32_16x16x32_bf16 v[100:103], v[218:221], v[194:197], v[100:103]
	v_mfma_f32_16x16x32_bf16 v[96:99], v[226:229], v[194:197], v[96:99]
	v_mfma_f32_16x16x32_bf16 v[84:87], v[218:221], v[202:205], v[84:87]
	v_mfma_f32_16x16x32_bf16 v[80:83], v[226:229], v[202:205], v[80:83]
	v_mfma_f32_16x16x32_bf16 v[68:71], v[218:221], v[210:213], v[68:71]
	v_mfma_f32_16x16x32_bf16 v[64:67], v[226:229], v[210:213], v[64:67]
	s_setprio 0
	s_mov_b32 m0, s34
	v_lshl_add_u64 v[150:151], v[232:233], 0, s[12:13]
	s_barrier
	ds_read_b128 v[182:185], v152 offset:49152
	ds_read_b128 v[186:189], v152 offset:50176
	ds_read_b128 v[190:193], v152 offset:51200
	ds_read_b128 v[194:197], v152 offset:52224
	ds_read_b128 v[198:201], v152 offset:53248
	ds_read_b128 v[202:205], v152 offset:54272
	ds_read_b128 v[206:209], v152 offset:55296
	ds_read_b128 v[210:213], v152 offset:56320
	global_load_lds_dwordx4 v[150:151], off
	v_lshl_add_u64 v[150:151], v[234:235], 0, s[12:13]
	s_mov_b32 m0, s35
	s_nop 0
	global_load_lds_dwordx4 v[150:151], off
	s_barrier
	s_waitcnt lgkmcnt(0)
	s_setprio 1
	s_waitcnt lgkmcnt(0)
	v_mfma_f32_16x16x32_bf16 v[60:63], v[146:149], v[182:185], v[60:63]
	v_mfma_f32_16x16x32_bf16 v[56:59], v[174:177], v[182:185], v[56:59]
	v_mfma_f32_16x16x32_bf16 v[44:47], v[146:149], v[190:193], v[44:47]
	v_mfma_f32_16x16x32_bf16 v[40:43], v[174:177], v[190:193], v[40:43]
	v_mfma_f32_16x16x32_bf16 v[28:31], v[146:149], v[198:201], v[28:31]
	v_mfma_f32_16x16x32_bf16 v[24:27], v[174:177], v[198:201], v[24:27]
	v_mfma_f32_16x16x32_bf16 v[12:15], v[146:149], v[206:209], v[12:15]
	v_mfma_f32_16x16x32_bf16 v[8:11], v[174:177], v[206:209], v[8:11]
	v_mfma_f32_16x16x32_bf16 v[60:63], v[170:173], v[186:189], v[60:63]
	v_mfma_f32_16x16x32_bf16 v[56:59], v[178:181], v[186:189], v[56:59]
	v_mfma_f32_16x16x32_bf16 v[44:47], v[170:173], v[194:197], v[44:47]
	v_mfma_f32_16x16x32_bf16 v[40:43], v[178:181], v[194:197], v[40:43]
	v_mfma_f32_16x16x32_bf16 v[28:31], v[170:173], v[202:205], v[28:31]
	v_mfma_f32_16x16x32_bf16 v[24:27], v[178:181], v[202:205], v[24:27]
	v_mfma_f32_16x16x32_bf16 v[12:15], v[170:173], v[210:213], v[12:15]
	v_mfma_f32_16x16x32_bf16 v[8:11], v[178:181], v[210:213], v[8:11]
	s_setprio 0
	s_barrier
	s_add_u32 s18, s18, 0x84080
	s_addc_u32 s19, s19, 0
	s_mov_b32 m0, s40
	v_lshl_add_u64 v[146:147], s[18:19], 0, v[130:131]
	global_load_lds_dwordx4 v[146:147], off
	v_lshl_add_u64 v[146:147], s[18:19], 0, v[132:133]
	s_mov_b32 m0, s41
	s_nop 0
	global_load_lds_dwordx4 v[146:147], off
	s_waitcnt vmcnt(6)
	s_barrier
	s_setprio 1
	v_mfma_f32_16x16x32_bf16 v[52:55], v[214:217], v[182:185], v[52:55]
	v_mfma_f32_16x16x32_bf16 v[48:51], v[222:225], v[182:185], v[48:51]
	v_mfma_f32_16x16x32_bf16 v[36:39], v[214:217], v[190:193], v[36:39]
	v_mfma_f32_16x16x32_bf16 v[32:35], v[222:225], v[190:193], v[32:35]
	v_mfma_f32_16x16x32_bf16 v[20:23], v[214:217], v[198:201], v[20:23]
	v_mfma_f32_16x16x32_bf16 v[16:19], v[222:225], v[198:201], v[16:19]
	v_mfma_f32_16x16x32_bf16 v[4:7], v[214:217], v[206:209], v[4:7]
	v_mfma_f32_16x16x32_bf16 v[0:3], v[222:225], v[206:209], v[0:3]
	v_mfma_f32_16x16x32_bf16 v[52:55], v[218:221], v[186:189], v[52:55]
	v_mfma_f32_16x16x32_bf16 v[48:51], v[226:229], v[186:189], v[48:51]
	v_mfma_f32_16x16x32_bf16 v[36:39], v[218:221], v[194:197], v[36:39]
	v_mfma_f32_16x16x32_bf16 v[32:35], v[226:229], v[194:197], v[32:35]
	v_mfma_f32_16x16x32_bf16 v[20:23], v[218:221], v[202:205], v[20:23]
	v_mfma_f32_16x16x32_bf16 v[16:19], v[226:229], v[202:205], v[16:19]
	v_mfma_f32_16x16x32_bf16 v[4:7], v[218:221], v[210:213], v[4:7]
	v_mfma_f32_16x16x32_bf16 v[0:3], v[226:229], v[210:213], v[0:3]
	s_setprio 0
	s_add_i32 s52, s52, 2
	s_add_u32 s6, s6, 0x100
	s_addc_u32 s7, s7, 0
	s_add_u32 s38, s38, 0x100
	s_addc_u32 s39, s39, 0
	s_cmp_gt_u32 s52, 29
	s_barrier
	s_cbranch_scc0 .LBB0_737
	s_cmp_eq_u32 s37, 0
	s_cbranch_scc1 .Lepi_out_slow
	s_cmp_eq_u32 s37, 64
	s_cbranch_scc1 .Lepi_out_slow
	s_cmp_lt_u32 s37, 0x88
	s_cbranch_scc0 .Lepi_out_slow
	s_lshl_b32 s6, s37, 8
	s_add_i32 s18, s6, s30
	s_cmp_lt_u32 s37, 64
	s_cselect_b32 s19, 16, 32
	s_sub_i32 s19, s18, s19
	v_add_u32_e32 v146, s19, v134
	v_add_u32_e32 v188, s18, v134
	v_lshlrev_b32_e32 v147, 12, v146
	v_lshlrev_b32_e32 v188, 2, v188
	v_lshrrev_b32_e32 v148, 2, v153
	v_and_b32_e32 v149, 1, v148
	v_bfe_u32 v150, v148, 1, 1
	v_and_b32_e32 v148, 0x60, v153
	v_lshlrev_b32_e32 v148, 1, v148
	v_lshl_add_u32 v148, v149, 5, v148
	v_lshl_add_u32 v148, v150, 4, v148
	s_lshl_b32 s6, s36, 9
	v_add3_u32 v147, v147, v148, s6
	v_mov_b32_e32 v151, s73
	v_add_co_u32_e32 v150, vcc, s72, v147
	v_xor_b32_e32 v186, 16, v129
	v_xor_b32_e32 v187, 32, v129
	v_addc_co_u32_e32 v151, vcc, 0, v151, vcc
	v_lshlrev_b32_e32 v186, 2, v186
	v_lshlrev_b32_e32 v187, 2, v187
	s_mov_b32 s20, 0x10000
	s_mov_b32 s21, 0
	s_mov_b32 s6, 0x50000
	s_mov_b32 s7, 0
	v_mul_f32_e32 v206, v125, v125
	v_mul_f32_e32 v207, v121, v121
	v_mul_f32_e32 v208, v117, v117
	v_mul_f32_e32 v209, v113, v113
	v_fmac_f32_e32 v206, v124, v124
	v_fmac_f32_e32 v207, v120, v120
	v_fmac_f32_e32 v208, v116, v116
	v_fmac_f32_e32 v209, v112, v112
	v_fmac_f32_e32 v206, v126, v126
	v_fmac_f32_e32 v207, v122, v122
	v_fmac_f32_e32 v208, v118, v118
	v_fmac_f32_e32 v209, v114, v114
	v_fmac_f32_e32 v206, v127, v127
	v_fmac_f32_e32 v207, v123, v123
	v_fmac_f32_e32 v208, v119, v119
	v_fmac_f32_e32 v209, v115, v115
	v_add_f32_e32 v170, v206, v207
	v_add_f32_e32 v170, v170, v208
	v_add_f32_e32 v170, v170, v209
	v_mul_f32_e32 v206, v109, v109
	v_mul_f32_e32 v207, v105, v105
	v_mul_f32_e32 v208, v101, v101
	v_mul_f32_e32 v209, v97, v97
	v_fmac_f32_e32 v206, v108, v108
	v_fmac_f32_e32 v207, v104, v104
	v_fmac_f32_e32 v208, v100, v100
	v_fmac_f32_e32 v209, v96, v96
	v_fmac_f32_e32 v206, v110, v110
	v_fmac_f32_e32 v207, v106, v106
	v_fmac_f32_e32 v208, v102, v102
	v_fmac_f32_e32 v209, v98, v98
	v_fmac_f32_e32 v206, v111, v111
	v_fmac_f32_e32 v207, v107, v107
	v_fmac_f32_e32 v208, v103, v103
	v_fmac_f32_e32 v209, v99, v99
	v_add_f32_e32 v171, v206, v207
	v_add_f32_e32 v171, v171, v208
	v_add_f32_e32 v171, v171, v209
	v_mul_f32_e32 v206, v93, v93
	v_mul_f32_e32 v207, v89, v89
	v_mul_f32_e32 v208, v85, v85
	v_mul_f32_e32 v209, v81, v81
	v_fmac_f32_e32 v206, v92, v92
	v_fmac_f32_e32 v207, v88, v88
	v_fmac_f32_e32 v208, v84, v84
	v_fmac_f32_e32 v209, v80, v80
	v_fmac_f32_e32 v206, v94, v94
	v_fmac_f32_e32 v207, v90, v90
	v_fmac_f32_e32 v208, v86, v86
	v_fmac_f32_e32 v209, v82, v82
	v_fmac_f32_e32 v206, v95, v95
	v_fmac_f32_e32 v207, v91, v91
	v_fmac_f32_e32 v208, v87, v87
	v_fmac_f32_e32 v209, v83, v83
	v_add_f32_e32 v172, v206, v207
	v_add_f32_e32 v172, v172, v208
	v_add_f32_e32 v172, v172, v209
	v_mul_f32_e32 v206, v77, v77
	v_mul_f32_e32 v207, v73, v73
	v_mul_f32_e32 v208, v69, v69
	v_mul_f32_e32 v209, v65, v65
	v_fmac_f32_e32 v206, v76, v76
	v_fmac_f32_e32 v207, v72, v72
	v_fmac_f32_e32 v208, v68, v68
	v_fmac_f32_e32 v209, v64, v64
	v_fmac_f32_e32 v206, v78, v78
	v_fmac_f32_e32 v207, v74, v74
	v_fmac_f32_e32 v208, v70, v70
	v_fmac_f32_e32 v209, v66, v66
	v_fmac_f32_e32 v206, v79, v79
	v_fmac_f32_e32 v207, v75, v75
	v_fmac_f32_e32 v208, v71, v71
	v_fmac_f32_e32 v209, v67, v67
	v_add_f32_e32 v173, v206, v207
	v_add_f32_e32 v173, v173, v208
	v_add_f32_e32 v173, v173, v209
	v_mul_f32_e32 v206, v61, v61
	v_mul_f32_e32 v207, v57, v57
	v_mul_f32_e32 v208, v53, v53
	v_mul_f32_e32 v209, v49, v49
	v_fmac_f32_e32 v206, v60, v60
	v_fmac_f32_e32 v207, v56, v56
	v_fmac_f32_e32 v208, v52, v52
	v_fmac_f32_e32 v209, v48, v48
	v_fmac_f32_e32 v206, v62, v62
	v_fmac_f32_e32 v207, v58, v58
	v_fmac_f32_e32 v208, v54, v54
	v_fmac_f32_e32 v209, v50, v50
	v_fmac_f32_e32 v206, v63, v63
	v_fmac_f32_e32 v207, v59, v59
	v_fmac_f32_e32 v208, v55, v55
	v_fmac_f32_e32 v209, v51, v51
	v_add_f32_e32 v174, v206, v207
	v_add_f32_e32 v174, v174, v208
	v_add_f32_e32 v174, v174, v209
	v_mul_f32_e32 v206, v45, v45
	v_mul_f32_e32 v207, v41, v41
	v_mul_f32_e32 v208, v37, v37
	v_mul_f32_e32 v209, v33, v33
	v_fmac_f32_e32 v206, v44, v44
	v_fmac_f32_e32 v207, v40, v40
	v_fmac_f32_e32 v208, v36, v36
	v_fmac_f32_e32 v209, v32, v32
	v_fmac_f32_e32 v206, v46, v46
	v_fmac_f32_e32 v207, v42, v42
	v_fmac_f32_e32 v208, v38, v38
	v_fmac_f32_e32 v209, v34, v34
	v_fmac_f32_e32 v206, v47, v47
	v_fmac_f32_e32 v207, v43, v43
	v_fmac_f32_e32 v208, v39, v39
	v_fmac_f32_e32 v209, v35, v35
	v_add_f32_e32 v175, v206, v207
	v_add_f32_e32 v175, v175, v208
	v_add_f32_e32 v175, v175, v209
	v_mul_f32_e32 v206, v29, v29
	v_mul_f32_e32 v207, v25, v25
	v_mul_f32_e32 v208, v21, v21
	v_mul_f32_e32 v209, v17, v17
	v_fmac_f32_e32 v206, v28, v28
	v_fmac_f32_e32 v207, v24, v24
	v_fmac_f32_e32 v208, v20, v20
	v_fmac_f32_e32 v209, v16, v16
	v_fmac_f32_e32 v206, v30, v30
	v_fmac_f32_e32 v207, v26, v26
	v_fmac_f32_e32 v208, v22, v22
	v_fmac_f32_e32 v209, v18, v18
	v_fmac_f32_e32 v206, v31, v31
	v_fmac_f32_e32 v207, v27, v27
	v_fmac_f32_e32 v208, v23, v23
	v_fmac_f32_e32 v209, v19, v19
	v_add_f32_e32 v176, v206, v207
	v_add_f32_e32 v176, v176, v208
	v_add_f32_e32 v176, v176, v209
	v_mul_f32_e32 v206, v13, v13
	v_mul_f32_e32 v207, v9, v9
	v_mul_f32_e32 v208, v5, v5
	v_mul_f32_e32 v209, v1, v1
	v_fmac_f32_e32 v206, v12, v12
	v_fmac_f32_e32 v207, v8, v8
	v_fmac_f32_e32 v208, v4, v4
	v_fmac_f32_e32 v209, v0, v0
	v_fmac_f32_e32 v206, v14, v14
	v_fmac_f32_e32 v207, v10, v10
	v_fmac_f32_e32 v208, v6, v6
	v_fmac_f32_e32 v209, v2, v2
	v_fmac_f32_e32 v206, v15, v15
	v_fmac_f32_e32 v207, v11, v11
	v_fmac_f32_e32 v208, v7, v7
	v_fmac_f32_e32 v209, v3, v3
	v_add_f32_e32 v177, v206, v207
	v_add_f32_e32 v177, v177, v208
	v_add_f32_e32 v177, v177, v209
	ds_bpermute_b32 v178, v186, v170
	ds_bpermute_b32 v179, v186, v171
	ds_bpermute_b32 v180, v186, v172
	ds_bpermute_b32 v181, v186, v173
	ds_bpermute_b32 v182, v186, v174
	ds_bpermute_b32 v183, v186, v175
	ds_bpermute_b32 v184, v186, v176
	ds_bpermute_b32 v185, v186, v177
	s_waitcnt lgkmcnt(0)
	v_add_f32_e32 v170, v170, v178
	v_add_f32_e32 v171, v171, v179
	v_add_f32_e32 v172, v172, v180
	v_add_f32_e32 v173, v173, v181
	v_add_f32_e32 v174, v174, v182
	v_add_f32_e32 v175, v175, v183
	v_add_f32_e32 v176, v176, v184
	v_add_f32_e32 v177, v177, v185
	ds_bpermute_b32 v178, v187, v170
	ds_bpermute_b32 v179, v187, v171
	ds_bpermute_b32 v180, v187, v172
	ds_bpermute_b32 v181, v187, v173
	ds_bpermute_b32 v182, v187, v174
	ds_bpermute_b32 v183, v187, v175
	ds_bpermute_b32 v184, v187, v176
	ds_bpermute_b32 v185, v187, v177
	v_cvt_pk_bf16_f32 v190, v124, v125
	v_cvt_pk_bf16_f32 v191, v126, v127
	v_cvt_pk_bf16_f32 v192, v120, v121
	v_cvt_pk_bf16_f32 v193, v122, v123
	v_cvt_pk_bf16_f32 v194, v116, v117
	v_cvt_pk_bf16_f32 v195, v118, v119
	v_cvt_pk_bf16_f32 v196, v112, v113
	v_cvt_pk_bf16_f32 v197, v114, v115
	s_nop 0
	v_permlane16_swap_b32_e32 v190, v192
	v_permlane16_swap_b32_e32 v191, v193
	v_permlane16_swap_b32_e32 v194, v196
	v_permlane16_swap_b32_e32 v195, v197
	s_nop 0
	global_store_dwordx4 v[150:151], v[190:193], off nt
	global_store_dwordx4 v[150:151], v[194:197], off offset:256 nt
	v_lshl_add_u64 v[150:151], v[150:151], 0, s[20:21]
	v_cvt_pk_bf16_f32 v198, v108, v109
	v_cvt_pk_bf16_f32 v199, v110, v111
	v_cvt_pk_bf16_f32 v200, v104, v105
	v_cvt_pk_bf16_f32 v201, v106, v107
	v_cvt_pk_bf16_f32 v202, v100, v101
	v_cvt_pk_bf16_f32 v203, v102, v103
	v_cvt_pk_bf16_f32 v204, v96, v97
	v_cvt_pk_bf16_f32 v205, v98, v99
	s_nop 0
	v_permlane16_swap_b32_e32 v198, v200
	v_permlane16_swap_b32_e32 v199, v201
	v_permlane16_swap_b32_e32 v202, v204
	v_permlane16_swap_b32_e32 v203, v205
	s_nop 0
	global_store_dwordx4 v[150:151], v[198:201], off nt
	global_store_dwordx4 v[150:151], v[202:205], off offset:256 nt
	v_lshl_add_u64 v[150:151], v[150:151], 0, s[20:21]
	v_cvt_pk_bf16_f32 v190, v92, v93
	v_cvt_pk_bf16_f32 v191, v94, v95
	v_cvt_pk_bf16_f32 v192, v88, v89
	v_cvt_pk_bf16_f32 v193, v90, v91
	v_cvt_pk_bf16_f32 v194, v84, v85
	v_cvt_pk_bf16_f32 v195, v86, v87
	v_cvt_pk_bf16_f32 v196, v80, v81
	v_cvt_pk_bf16_f32 v197, v82, v83
	s_nop 0
	v_permlane16_swap_b32_e32 v190, v192
	v_permlane16_swap_b32_e32 v191, v193
	v_permlane16_swap_b32_e32 v194, v196
	v_permlane16_swap_b32_e32 v195, v197
	s_nop 0
	global_store_dwordx4 v[150:151], v[190:193], off nt
	global_store_dwordx4 v[150:151], v[194:197], off offset:256 nt
	v_lshl_add_u64 v[150:151], v[150:151], 0, s[20:21]
	v_cvt_pk_bf16_f32 v198, v76, v77
	v_cvt_pk_bf16_f32 v199, v78, v79
	v_cvt_pk_bf16_f32 v200, v72, v73
	v_cvt_pk_bf16_f32 v201, v74, v75
	v_cvt_pk_bf16_f32 v202, v68, v69
	v_cvt_pk_bf16_f32 v203, v70, v71
	v_cvt_pk_bf16_f32 v204, v64, v65
	v_cvt_pk_bf16_f32 v205, v66, v67
	s_nop 0
	v_permlane16_swap_b32_e32 v198, v200
	v_permlane16_swap_b32_e32 v199, v201
	v_permlane16_swap_b32_e32 v202, v204
	v_permlane16_swap_b32_e32 v203, v205
	s_nop 0
	global_store_dwordx4 v[150:151], v[198:201], off nt
	global_store_dwordx4 v[150:151], v[202:205], off offset:256 nt
	v_lshl_add_u64 v[150:151], v[150:151], 0, s[6:7]
	v_cvt_pk_bf16_f32 v190, v60, v61
	v_cvt_pk_bf16_f32 v191, v62, v63
	v_cvt_pk_bf16_f32 v192, v56, v57
	v_cvt_pk_bf16_f32 v193, v58, v59
	v_cvt_pk_bf16_f32 v194, v52, v53
	v_cvt_pk_bf16_f32 v195, v54, v55
	v_cvt_pk_bf16_f32 v196, v48, v49
	v_cvt_pk_bf16_f32 v197, v50, v51
	s_nop 0
	v_permlane16_swap_b32_e32 v190, v192
	v_permlane16_swap_b32_e32 v191, v193
	v_permlane16_swap_b32_e32 v194, v196
	v_permlane16_swap_b32_e32 v195, v197
	s_nop 0
	global_store_dwordx4 v[150:151], v[190:193], off nt
	global_store_dwordx4 v[150:151], v[194:197], off offset:256 nt
	v_lshl_add_u64 v[150:151], v[150:151], 0, s[20:21]
	v_cvt_pk_bf16_f32 v198, v44, v45
	v_cvt_pk_bf16_f32 v199, v46, v47
	v_cvt_pk_bf16_f32 v200, v40, v41
	v_cvt_pk_bf16_f32 v201, v42, v43
	v_cvt_pk_bf16_f32 v202, v36, v37
	v_cvt_pk_bf16_f32 v203, v38, v39
	v_cvt_pk_bf16_f32 v204, v32, v33
	v_cvt_pk_bf16_f32 v205, v34, v35
	s_nop 0
	v_permlane16_swap_b32_e32 v198, v200
	v_permlane16_swap_b32_e32 v199, v201
	v_permlane16_swap_b32_e32 v202, v204
	v_permlane16_swap_b32_e32 v203, v205
	s_nop 0
	global_store_dwordx4 v[150:151], v[198:201], off nt
	global_store_dwordx4 v[150:151], v[202:205], off offset:256 nt
	v_lshl_add_u64 v[150:151], v[150:151], 0, s[20:21]
	v_cvt_pk_bf16_f32 v190, v28, v29
	v_cvt_pk_bf16_f32 v191, v30, v31
	v_cvt_pk_bf16_f32 v192, v24, v25
	v_cvt_pk_bf16_f32 v193, v26, v27
	v_cvt_pk_bf16_f32 v194, v20, v21
	v_cvt_pk_bf16_f32 v195, v22, v23
	v_cvt_pk_bf16_f32 v196, v16, v17
	v_cvt_pk_bf16_f32 v197, v18, v19
	s_nop 0
	v_permlane16_swap_b32_e32 v190, v192
	v_permlane16_swap_b32_e32 v191, v193
	v_permlane16_swap_b32_e32 v194, v196
	v_permlane16_swap_b32_e32 v195, v197
	s_nop 0
	global_store_dwordx4 v[150:151], v[190:193], off nt
	global_store_dwordx4 v[150:151], v[194:197], off offset:256 nt
	v_lshl_add_u64 v[150:151], v[150:151], 0, s[20:21]
	v_cvt_pk_bf16_f32 v198, v12, v13
	v_cvt_pk_bf16_f32 v199, v14, v15
	v_cvt_pk_bf16_f32 v200, v8, v9
	v_cvt_pk_bf16_f32 v201, v10, v11
	v_cvt_pk_bf16_f32 v202, v4, v5
	v_cvt_pk_bf16_f32 v203, v6, v7
	v_cvt_pk_bf16_f32 v204, v0, v1
	v_cvt_pk_bf16_f32 v205, v2, v3
	s_nop 0
	v_permlane16_swap_b32_e32 v198, v200
	v_permlane16_swap_b32_e32 v199, v201
	v_permlane16_swap_b32_e32 v202, v204
	v_permlane16_swap_b32_e32 v203, v205
	s_nop 0
	global_store_dwordx4 v[150:151], v[198:201], off nt
	global_store_dwordx4 v[150:151], v[202:205], off offset:256 nt
	s_waitcnt lgkmcnt(0)
	v_add_f32_e32 v170, v170, v178
	v_add_f32_e32 v171, v171, v179
	v_add_f32_e32 v172, v172, v180
	v_add_f32_e32 v173, v173, v181
	v_add_f32_e32 v174, v174, v182
	v_add_f32_e32 v175, v175, v183
	v_add_f32_e32 v176, v176, v184
	v_add_f32_e32 v177, v177, v185
	s_mov_b64 exec, s[10:11]
	global_atomic_add_f32 v188, v170, s[88:89]
	global_atomic_add_f32 v188, v171, s[88:89] offset:64
	global_atomic_add_f32 v188, v172, s[88:89] offset:128
	global_atomic_add_f32 v188, v173, s[88:89] offset:192
	global_atomic_add_f32 v188, v174, s[88:89] offset:512
	global_atomic_add_f32 v188, v175, s[88:89] offset:576
	global_atomic_add_f32 v188, v176, s[88:89] offset:640
	global_atomic_add_f32 v188, v177, s[88:89] offset:704
	s_mov_b64 exec, -1
	s_branch .LBB0_729
